# v041 + phase prologues copy the workspace base from s[26:27] instead of re-loading kernarg 0xb8 after each grid barrier
# baseline (speedup 1.0000x reference)
; __global__ void __launch_bounds__(512, 2) fwd_mega(Args a) {
;     ...
;         float* cs = (float*)lds_raw; float* red = cs + 4096;
;         for (int u = bx; u < 192; u += G) {
;             const int l = u / 96, cb = u % 96;
;             for (int i = tid; i < 4096; i += 512) { const float v = INF(1)[i]; cs[i] = v / (1.f + __expf(-v)); }
;             __syncthreads();
;             const int kg = tid >> 6, col = tid & 63, j = cb * 64 + col;
;             const float* w = INF(3) + (size_t)l * 1024 * 6144 + (size_t)(kg * 128) * 6144 + j;
;             float a0 = 0.f, a1 = 0.f, a2 = 0.f, a3 = 0.f;
; #pragma unroll 32
;             for (int k = 0; k < 128; ++k) { const float wv = w[(size_t)k * 6144]; const int kk = kg * 128 + k; a0 += cs[kk] * wv; a1 += cs[1024 + kk] * wv; a2 += cs[2048 + kk] * wv; a3 += cs[3072 + kk] * wv; }
;             red[(kg * 4 + 0) * 64 + col] = a0; red[(kg * 4 + 1) * 64 + col] = a1; red[(kg * 4 + 2) * 64 + col] = a2; red[(kg * 4 + 3) * 64 + col] = a3;
;             __syncthreads();
;             if (tid < 256) { const int b = tid >> 6, cc = tid & 63; float s = 0.f;
; #pragma unroll
;                 for (int q = 0; q < 8; ++q) s += red[(q * 4 + b) * 64 + cc];
;                 ((float*)(a.ws + WS_MOD))[(size_t)(l * 4 + b) * 6144 + cb * 64 + cc] = s + INF(4)[l * 6144 + cb * 64 + cc]; }
;             __syncthreads();
.LBB0_5:
	s_or_b64 exec, exec, s[4:5]
	s_cmpk_gt_i32 s2, 0xbf
	v_and_b32_e32 v114, 63, v0
	s_cbranch_scc1 .LBB0_14
	s_load_dwordx2 s[10:11], s[0:1], 0x8
	s_load_dwordx4 s[4:7], s[0:1], 0x18
	s_mov_b64 s[8:9], s[26:27]
	v_mul_u32_u24_e32 v3, 0xc0000, v1
	v_lshlrev_b32_e32 v116, 2, v3
	v_mov_b32_e32 v117, 0
	v_lshl_add_u32 v2, v114, 2, 0
	s_waitcnt lgkmcnt(0)
	v_lshl_add_u64 v[118:119], s[4:5], 0, v[116:117]
	v_lshlrev_b32_e32 v3, 10, v1
	s_movk_i32 s4, 0x100
	v_and_b32_e32 v4, 0xc0, v0
	v_lshlrev_b32_e32 v116, 2, v0
	v_lshl_add_u32 v115, v1, 9, 0
	v_cmp_gt_u32_e64 s[4:5], s4, v0
	v_lshl_add_u32 v130, v4, 2, v2
	v_or_b32_e32 v131, 0xfffffe00, v0
	v_lshl_add_u64 v[120:121], s[10:11], 0, v[116:117]
	v_add_u32_e32 v132, 0, v116
	s_mov_b64 s[10:11], 0x800
	s_movk_i32 s16, 0xdff
	v_mov_b32_e32 v133, 0x1800000
	s_movk_i32 s17, 0x6000
	s_mov_b32 s18, 0xc000
	s_mov_b32 s19, 0x12000
	s_mov_b32 s20, 0x18000
	s_mov_b32 s21, 0x1e000
	s_mov_b32 s22, 0x24000
	s_mov_b32 s23, 0x2a000
	s_mov_b32 s25, 0x30000
	s_mov_b32 s28, 0x36000
	s_mov_b32 s29, 0x3c000
	s_mov_b32 s30, 0x42000
	s_mov_b32 s31, 0x48000
	s_mov_b32 s34, 0x4e000
	s_mov_b32 s35, 0x54000
	s_mov_b32 s36, 0x5a000
	s_mov_b32 s37, 0x60000
	s_mov_b32 s38, 0x66000
	s_mov_b32 s39, 0x6c000
	s_mov_b32 s40, 0x72000
	s_mov_b32 s41, 0x78000
	s_mov_b32 s42, 0x7e000
	s_mov_b32 s43, 0x84000
	s_mov_b32 s44, 0x8a000
	s_mov_b32 s45, 0x90000
	s_mov_b32 s46, 0x96000
	s_mov_b32 s47, 0x9c000
	s_mov_b32 s48, 0xa2000
	s_mov_b32 s49, 0xa8000
	s_mov_b32 s50, 0xae000
	s_mov_b32 s51, 0xb4000
	s_mov_b32 s52, 0xba000
	v_add_u32_e32 v134, v2, v3
	v_lshlrev_b32_e32 v116, 2, v114
	s_mov_b32 s53, s2
	s_branch .LBB0_8

; __global__ void __launch_bounds__(512, 2) fwd_mega(Args a) {
;     ...
;         for (int row = gtid; row < M; row += NTH) {
;             const float p = (float)((const int*)a.in[2])[row];
; #pragma unroll
;             for (int d = 0; d < 8; ++d) { const float ang = p * a.invf[d]; const double rev = (double)ang * 0.15915494309189535; const float f = (float)(rev - rint(rev));
;                 ((float*)(a.ws + WS_ROPE))[(size_t)row * 16 + d] = __builtin_amdgcn_cosf(f); ((float*)(a.ws + WS_ROPE))[(size_t)row * 16 + 8 + d] = __builtin_amdgcn_sinf(f); }
;         }
.LBB0_14:
	v_lshl_or_b32 v2, s2, 9, v0
	s_movk_i32 s4, 0x4000
	v_cmp_gt_i32_e32 vcc, s4, v2
	s_and_saveexec_b64 s[12:13], vcc
	s_cbranch_execz .LBB0_17
	s_load_dwordx2 s[16:17], s[0:1], 0x10
	s_mov_b64 s[18:19], s[26:27]
	s_load_dwordx8 s[4:11], s[0:1], 0xc0
	v_ashrrev_i32_e32 v3, 31, v2
	s_lshl_b32 s14, s3, 9
	v_lshlrev_b64 v[6:7], 6, v[2:3]
	s_ashr_i32 s15, s14, 31
	s_waitcnt lgkmcnt(0)
	v_lshl_add_u64 v[6:7], s[18:19], 0, v[6:7]
	s_mov_b64 s[18:19], 0x100000
	s_mov_b32 s22, 0x6dc9c883
	v_lshl_add_u64 v[4:5], v[2:3], 2, s[16:17]
	s_lshl_b64 s[16:17], s[14:15], 2
	v_lshl_add_u64 v[6:7], v[6:7], 0, s[18:19]
	s_lshl_b64 s[18:19], s[14:15], 6
	s_mov_b64 s[20:21], 0
	s_mov_b32 s23, 0x3fc45f30
	s_movk_i32 s15, 0x3fff

; __device__ __forceinline__ void tr_item(const float* W, int N, bf16* WT, int dpitch, int koff, int drow0, int k0, int n0, LAS float* scr, int lane) {
;     float tv[32];
; #pragma unroll
;     for (int i = 0; i < 32; ++i) tv[i] = W[(size_t)(k0 + 2 * i + (lane >> 5)) * N + n0 + (lane & 31)];
; #pragma unroll
;     for (int i = 0; i < 32; ++i) scr[(2 * i + (lane >> 5)) * 33 + (lane & 31)] = tv[i];
;     LDS_WAIT(); asm volatile("" ::: "memory");
;     const int c = lane & 7;
; #pragma unroll
;     for (int j = 0; j < 4; ++j) { const int n = (lane >> 3) + 8 * j; const LAS float* s = scr + (8 * c) * 33 + n;
; __global__ void __launch_bounds__(512, 2) fwd_mega(Args a) {
;     ...
;     auto convert_items = [&](int LL, int lo, int hi, int w0, int nw_, size_t wd_off) __attribute__((always_inline)) {
;         LAS float* scr = (LAS float*)(lds + wave * 16384);
;         for (int it0 = lo + w0; it0 < hi; it0 += nw_) {
;             int it = it0;
;             if (it < 2688) { const int kb = it / 168, nb = it % 168; tr_item(INF(6) + (size_t)LL * D * INC, INC, WSP(WS_WIN), 1024, 0, 32 * nb, 64 * kb, 32 * nb, scr, lane); continue; } it -= 2688;
;             if (it < 512) { const int kb = it / 32, nb = it % 32; tr_item(INF(13) + (size_t)LL * D * D, D, WSP(WS_PAB), 1024, 0, 32 * nb, 64 * kb, 32 * nb, scr, lane); continue; } it -= 512;
;             if (it < 512) { const int kb = it / 32, nb = it % 32; tr_item(INF(12) + (size_t)LL * D * D, D, WSP(WS_PAB), 1024, 0, 1024 + 32 * nb, 64 * kb, 32 * nb, scr, lane); continue; } it -= 512;
;             if (it < 512) { const int kb = it / 32, nb = it % 32; tr_item(INF(14) + (size_t)LL * D * D, D, WSP(WS_WO2), 1024, 0, 32 * nb, 64 * kb, 32 * nb, scr, lane); continue; } it -= 512;
;             if (it < 1408) { const int kb = it / 88, nb = it % 88, n0 = 32 * nb; tr_item(INF(16) + (size_t)LL * D * FF, FF, WSP(WS_WGU), 1024, 0, (n0 >> 7) * 256 + (n0 & 127), 64 * kb, n0, scr, lane); continue; } it -= 1408;
;             if (it < 1408) { const int kb = it / 88, nb = it % 88, n0 = 32 * nb; tr_item(INF(17) + (size_t)LL * D * FF, FF, WSP(WS_WGU), 1024, 0, (n0 >> 7) * 256 + 128 + (n0 & 127), 64 * kb, n0, scr, lane); continue; } it -= 1408;
;             { const int kb = it / 32, nb = it % 32; tr_item(INF(20) + (size_t)LL * FF * D, D, WSP(wd_off), 2816, 0, 32 * nb, 64 * kb, 32 * nb, scr, lane); }
;         }
;     };
.LBB0_17:
	s_or_b64 exec, exec, s[12:13]
	s_lshl_b32 s4, s2, 3
	v_writelane_b32 v246, s4, 2
	s_add_i32 s22, s24, s4
	s_lshl_b32 s4, s24, 14
	s_lshl_b32 s77, s3, 3
	s_add_i32 s4, s4, 0
	s_cmpk_lt_i32 s22, 0x2100
	v_writelane_b32 v246, s4, 3
	s_cselect_b64 s[6:7], -1, 0
	s_mov_b32 s5, 0
	v_writelane_b32 v246, s6, 4
	s_cmpk_gt_i32 s22, 0x20ff
	v_lshrrev_b32_e32 v200, 5, v114
	v_and_b32_e32 v205, 31, v0
	v_lshrrev_b32_e32 v201, 3, v114
	v_lshlrev_b32_e32 v204, 3, v0
	v_writelane_b32 v246, s7, 5
	s_cbranch_scc1 .LBB0_44
	s_load_dwordx2 s[6:7], s[0:1], 0xa0
	s_mov_b64 s[8:9], s[26:27]
	v_mov_b32_e32 v3, 0
	v_and_b32_e32 v6, 56, v204
	v_mul_u32_u24_e32 v8, 0x84, v6
	v_lshlrev_b32_e32 v6, 1, v6
	v_mov_b32_e32 v7, v3
	s_waitcnt lgkmcnt(0)
	v_lshl_add_u64 v[26:27], s[8:9], 0, v[6:7]
	s_load_dwordx4 s[8:11], s[0:1], 0x80
	v_lshlrev_b32_e32 v2, 2, v205
	v_lshl_add_u64 v[4:5], s[6:7], 0, v[2:3]
	s_mov_b64 s[6:7], 0x2580000
	v_lshl_add_u64 v[6:7], v[26:27], 0, s[6:7]
	s_load_dwordx2 s[6:7], s[0:1], 0x70
	v_readlane_b32 s4, v246, 3
	v_lshlrev_b32_e32 v9, 2, v201
	s_waitcnt lgkmcnt(0)
	v_lshl_add_u64 v[12:13], s[8:9], 0, v[2:3]
	v_add3_u32 v28, s4, v8, v9
	v_lshl_add_u64 v[8:9], s[10:11], 0, v[2:3]
	s_mov_b64 s[10:11], 0x1a80000
	v_lshl_add_u64 v[10:11], v[26:27], 0, s[10:11]
	s_load_dwordx2 s[12:13], s[0:1], 0x30
	s_load_dwordx4 s[8:11], s[0:1], 0x60
	v_lshl_add_u64 v[14:15], s[6:7], 0, v[2:3]
	s_mov_b64 s[6:7], 0x1680000
	v_mul_u32_u24_e32 v1, 0x84, v200
	v_lshl_add_u64 v[16:17], v[26:27], 0, s[6:7]
	s_mov_b64 s[6:7], 0x1280000
	v_add3_u32 v1, s4, v2, v1
	v_lshl_add_u64 v[20:21], v[26:27], 0, s[6:7]
	s_mov_b64 s[6:7], 0x800000
	v_or_b32_e32 v29, 8, v201
	v_or_b32_e32 v30, 16, v201
	v_or_b32_e32 v31, 24, v201
	s_waitcnt lgkmcnt(0)
	v_lshl_add_u64 v[18:19], s[8:9], 0, v[2:3]
	v_lshl_add_u64 v[22:23], s[10:11], 0, v[2:3]
	v_lshl_add_u64 v[24:25], s[12:13], 0, v[2:3]
	v_lshl_add_u64 v[26:27], v[26:27], 0, s[6:7]
	s_lshl_b32 s10, s22, 5
	s_lshl_b32 s11, s77, 5
	s_lshl_b32 s12, s22, 1
	s_lshl_b32 s13, s77, 1
	s_movk_i32 s14, 0x7fff
	s_mov_b32 s15, 0xffff0000
	s_movk_i32 s16, 0x5000
	s_mov_b32 s17, 0xb000
	s_mov_b32 s18, 0x10000
	s_mov_b32 s19, 0x16000
	s_mov_b32 s20, 0x1b000
	s_mov_b32 s21, 0x21000
	s_mov_b32 s23, 0x26000
	s_mov_b32 s24, 0x2c000
	s_mov_b32 s25, 0x31000
	s_mov_b32 s28, 0x37000
	s_mov_b32 s29, 0x3c000
	s_mov_b32 s30, 0x42000
	s_mov_b32 s31, 0x47000
	s_mov_b32 s34, 0x4d000
	s_mov_b32 s35, 0x52000
	s_mov_b32 s36, 0x58000
	s_mov_b32 s37, 0x5d000
	s_mov_b32 s38, 0x63000
	s_mov_b32 s39, 0x68000
	s_mov_b32 s40, 0x6e000
	s_mov_b32 s41, 0x73000
	s_mov_b32 s42, 0x79000
	s_mov_b32 s43, 0x7e000
	s_mov_b32 s44, 0x84000
	s_mov_b32 s45, 0x89000
	s_mov_b32 s46, 0x8f000
	s_mov_b32 s47, 0x94000
	s_mov_b32 s48, 0x9a000
	s_mov_b32 s49, 0x9f000
	s_mov_b32 s50, 0xa5000
	s_mov_b32 s51, 0xaa000
	s_movk_i32 s52, 0x5400
	v_add_u32_e32 v32, 0x400, v1
	v_add_u32_e32 v33, 0x800, v1
	v_add_u32_e32 v34, 0xc00, v1
	v_add_u32_e32 v35, 0x1000, v1
	v_add_u32_e32 v36, 0x1400, v1
	v_add_u32_e32 v37, 0x1800, v1
	v_add_u32_e32 v38, 0x1c00, v1
	s_mov_b32 s53, s22
	s_branch .LBB0_20

; __device__ __forceinline__ unsigned cvt_pk_bf16(float lo, float hi) { unsigned r; asm volatile("v_cvt_pk_bf16_f32 %0, %1, %2" : "=v"(r) : "v"(lo), "v"(hi)); return r; }
; __device__ __forceinline__ void sgu_wfrag_item(const float* Wl, v4u* WF, int item, int lane) {
;     const int g = item / 20, q = item % 20, fr = lane & 15, fq = lane >> 4;
;     int mt = 0, ks = 0, c = 0;
;     for (int m = 0; m < 8; ++m) for (int k = 0; k <= (m >> 1); ++k) { if (c == q) { mt = m; ks = k; } ++c; }
;     const int t = 16 * mt + fr, sb = 32 * ks + 8 * fq;
;     const float* p = Wl + ((size_t)g * 128 + t) * 128 + sb;
;     const f32x4 wa = *(const f32x4*)p, wb = *(const f32x4*)(p + 4);
;     v4u ww;
;     ww.x = cvt_pk_bf16(sb + 0 <= t ? wa.x : 0.f, sb + 1 <= t ? wa.y : 0.f); ww.y = cvt_pk_bf16(sb + 2 <= t ? wa.z : 0.f, sb + 3 <= t ? wa.w : 0.f);
;     ww.z = cvt_pk_bf16(sb + 4 <= t ? wb.x : 0.f, sb + 5 <= t ? wb.y : 0.f); ww.w = cvt_pk_bf16(sb + 6 <= t ? wb.z : 0.f, sb + 7 <= t ? wb.w : 0.f);
;     WF[(size_t)item * 64 + lane] = ww;
; }
; __global__ void __launch_bounds__(512, 2) fwd_mega(Args a) {
;     ...
;             for (int it = gw; it < 160; it += NGW) sgu_wfrag_item(INF(10), (v4u*)(a.ws + WS_WF), it, lane);
.LBB0_44:
	s_cmpk_lt_i32 s22, 0xa0
	s_cselect_b64 s[4:5], -1, 0
	v_writelane_b32 v246, s4, 6
	s_cmpk_gt_i32 s22, 0x9f
	v_and_b32_e32 v202, 15, v0
	v_lshrrev_b32_e32 v203, 1, v0
	v_lshlrev_b32_e32 v172, 4, v114
	v_writelane_b32 v246, s5, 7
	s_cbranch_scc1 .LBB0_47
	s_mov_b64 s[4:5], s[26:27]
	s_load_dwordx2 s[18:19], s[0:1], 0x50
	v_mov_b32_e32 v3, 0
	v_mov_b32_e32 v173, v3
	v_and_b32_e32 v1, 24, v203
	s_waitcnt lgkmcnt(0)
	v_lshl_add_u64 v[4:5], s[4:5], 0, v[172:173]
	s_mov_b64 s[4:5], 0x680000
	v_lshl_add_u64 v[4:5], v[4:5], 0, s[4:5]
	s_mov_b32 s20, s22

; __device__ __forceinline__ unsigned cvt_pk_bf16(float lo, float hi) { unsigned r; asm volatile("v_cvt_pk_bf16_f32 %0, %1, %2" : "=v"(r) : "v"(lo), "v"(hi)); return r; }
; __global__ void __launch_bounds__(512, 2) fwd_mega(Args a) {
;     ...
;             const float* xin = (l == 0) ? INF(0) : a.out; const float* nw = INF(5) + l * D; const float* ml = (const float*)(a.ws + WS_MOD) + (size_t)l * 4 * 6144;
;             for (int m0 = gw; m0 < M; m0 += 2 * NGW) {
;                 const int m1 = m0 + NGW; const bool has1 = m1 < M; const int m1c = has1 ? m1 : m0;
;                 const f32x4* xr0 = (const f32x4*)(xin + (size_t)m0 * D) + lane; const f32x4* xr1 = (const f32x4*)(xin + (size_t)m1c * D) + lane;
;                 f32x4 v0[4], v1[4]; float ss0 = 0.f, ss1 = 0.f;
; #pragma unroll
;                 for (int j = 0; j < 4; ++j) { v0[j] = xr0[64 * j]; v1[j] = xr1[64 * j]; }
; #pragma unroll
;                 for (int j = 0; j < 4; ++j) { ss0 += (v0[j].x * v0[j].x + v0[j].y * v0[j].y) + (v0[j].z * v0[j].z + v0[j].w * v0[j].w); ss1 += (v1[j].x * v1[j].x + v1[j].y * v1[j].y) + (v1[j].z * v1[j].z + v1[j].w * v1[j].w); }
;                 const float rstd0 = rsqrtf(wave_sum(ss0) * (1.f / D) + 1e-6f), rstd1 = rsqrtf(wave_sum(ss1) * (1.f / D) + 1e-6f);
;                 const int b0 = m0 >> 12, b1 = m1c >> 12;
;                 v2u* o0 = (v2u*)(WSP(WS_H) + (size_t)m0 * D) + lane; v2u* o1 = (v2u*)(WSP(WS_H) + (size_t)m1c * D) + lane;
; #pragma unroll
;                 for (int j = 0; j < 4; ++j) { const int col = 4 * lane + 256 * j; const f32x4 wv = *(const f32x4*)(nw + col);
;                     const f32x4 sh0 = *(const f32x4*)(ml + (size_t)b0 * 6144 + col), sc0 = *(const f32x4*)(ml + (size_t)b0 * 6144 + 1024 + col);
;                     const f32x4 sh1 = *(const f32x4*)(ml + (size_t)b1 * 6144 + col), sc1 = *(const f32x4*)(ml + (size_t)b1 * 6144 + 1024 + col);
;                     const f32x4 y0 = (v0[j] * rstd0) * wv * (sc0 + 1.0f) + sh0, y1 = (v1[j] * rstd1) * wv * (sc1 + 1.0f) + sh1;
;                     v2u w0; w0.x = cvt_pk_bf16(y0.x, y0.y); w0.y = cvt_pk_bf16(y0.z, y0.w); o0[64 * j] = w0;
;                     if (has1) { v2u w1; w1.x = cvt_pk_bf16(y1.x, y1.y); w1.y = cvt_pk_bf16(y1.z, y1.w); o1[64 * j] = w1; } }
;             }
.LBB0_99:
	s_or_b64 exec, exec, s[4:5]
	s_cmpk_gt_i32 s22, 0x3fff
	s_waitcnt lgkmcnt(0)
	v_mbcnt_lo_u32_b32 v1, -1, 0
	s_barrier
	s_cbranch_scc1 .LBB0_110
	v_mbcnt_hi_u32_b32 v2, -1, v1
	v_and_b32_e32 v3, 64, v2
	v_add_u32_e32 v3, 64, v3
	v_xor_b32_e32 v4, 1, v2
	v_cmp_lt_i32_e32 vcc, v4, v3
	s_mov_b64 s[6:7], s[26:27]
	s_load_dwordx2 s[4:5], s[0:1], 0x0
	s_load_dwordx2 s[8:9], s[0:1], 0x28
	v_cndmask_b32_e32 v4, v2, v4, vcc
	v_lshlrev_b32_e32 v57, 2, v4
	v_xor_b32_e32 v4, 2, v2
	v_cmp_lt_i32_e32 vcc, v4, v3
	v_mov_b32_e32 v173, 0
	s_ashr_i32 s23, s22, 31
	v_cndmask_b32_e32 v4, v2, v4, vcc
	v_lshlrev_b32_e32 v66, 2, v4
	v_xor_b32_e32 v4, 4, v2
	v_cmp_lt_i32_e32 vcc, v4, v3
	s_waitcnt lgkmcnt(0)
	v_lshl_add_u64 v[50:51], s[8:9], 0, v[172:173]
	s_lshl_b32 s8, s3, 4
	v_cndmask_b32_e32 v4, v2, v4, vcc
	v_lshlrev_b32_e32 v67, 2, v4
	v_xor_b32_e32 v4, 8, v2
	v_cmp_lt_i32_e32 vcc, v4, v3
	s_lshl_b64 s[10:11], s[22:23], 12
	v_lshl_add_u64 v[46:47], s[4:5], 0, v[172:173]
	v_cndmask_b32_e32 v4, v2, v4, vcc
	v_lshlrev_b32_e32 v68, 2, v4
	v_xor_b32_e32 v4, 16, v2
	v_cmp_lt_i32_e32 vcc, v4, v3
	s_add_u32 s4, s4, s10
	s_addc_u32 s5, s5, s11
	v_cndmask_b32_e32 v4, v2, v4, vcc
	v_lshlrev_b32_e32 v69, 2, v4
	v_xor_b32_e32 v4, 32, v2
	v_cmp_lt_i32_e32 vcc, v4, v3
	s_ashr_i32 s9, s8, 31
	v_mov_b32_e32 v3, v173
	v_cndmask_b32_e32 v2, v2, v4, vcc
	v_lshlrev_b32_e32 v70, 2, v2
	v_lshlrev_b32_e32 v2, 3, v114
	v_lshl_add_u64 v[52:53], s[4:5], 0, v[172:173]
	s_lshl_b64 s[10:11], s[8:9], 12
	s_lshl_b64 s[4:5], s[22:23], 11
	v_lshl_add_u64 v[4:5], s[6:7], 0, v[2:3]
	s_mov_b64 s[12:13], 0x2b00000
	s_add_u32 s4, s6, s4
	v_lshl_add_u64 v[48:49], v[4:5], 0, s[12:13]
	v_lshlrev_b32_e32 v4, 2, v114
	s_addc_u32 s5, s7, s5
	v_or_b32_e32 v6, 0x100, v4
	v_or_b32_e32 v8, 0x200, v4
	v_or_b32_e32 v10, 0x300, v4
	v_lshl_add_u64 v[2:3], s[4:5], 0, v[2:3]
	v_lshl_add_u64 v[54:55], v[2:3], 0, s[12:13]
	s_lshl_b64 s[12:13], s[8:9], 11
	s_mov_b32 s14, 0x3a800000
	v_mov_b32_e32 v56, 0x358637bd
	s_mov_b32 s9, 0x800000
	v_lshlrev_b32_e32 v58, 2, v4
	v_mov_b32_e32 v59, v173
	v_lshlrev_b32_e32 v71, 2, v6
	v_lshlrev_b32_e32 v72, 2, v8
	v_lshlrev_b32_e32 v73, 2, v10
	s_mov_b32 s15, s22
	s_branch .LBB0_102

; #define PG8_WAIT_V(n) asm volatile("s_waitcnt vmcnt(" #n ")" ::: "memory")
; template <class Epi, class Sched, bool ALIGN_EPI = false, bool SP2 = false, bool PAIR_ACC = false>
; __device__ __forceinline__ void gemm_phase(PG8_LAS unsigned char* lds, const Gemm g, const Sched& S, const Epi& E) {
;     ...
;     const int tid = tid_, wid = __builtin_amdgcn_readfirstlane(tid >> 6), lane = tid & 63, wr = wid >> 2, wc = wid & 3, fr = lane & 15, fq = lane >> 4;
;     const int K = g.K, nt = K / BK;
;     unsigned voffA[2], voffB[2];
; #pragma unroll
;     for (int i = 0; i < 2; ++i) { int R, C; stage_rc(tid * 16 + i * 8192, R, C); const int Rb = Epi::PERM ? ((R & ~31) + perm32(R & 31)) : R;
;         voffA[i] = (unsigned)(R * K + C) * 2u; voffB[i] = (unsigned)(Rb * K + C) * 2u; }
;     const size_t kstep = (size_t)(BK * 2);
;     const size_t hstep = (size_t)HALF * K * 2;
;     const size_t tstep = 2 * hstep;
;     const unsigned ldsw = (unsigned)wid * 1024u;
;     const int aoff = lds_byte(wr * 64 + fr, fq * 8), boff = lds_byte(wc * 32 + fr, fq * 8);
;     ...
;     Unit cur, nxt; int ui = 0;
;     if (!S.next(0, cur)) return;
;     f32x4 acc[2][2][4][2];
; #pragma unroll
;     for (int a = 0; a < 2; ++a)
; #pragma unroll
;         for (int b = 0; b < 2; ++b)
; #pragma unroll
;             for (int m = 0; m < 4; ++m)
; #pragma unroll
;                 for (int n = 0; n < 2; ++n) acc[a][b][m][n] = (f32x4){0.f, 0.f, 0.f, 0.f};
;     bf16x8 At[4][2], B0[2][2], B1[2][2];
;     const char* cA = (const char*)g.A + (size_t)cur.pm * tstep + (size_t)(cur.pn / g.a_div) * g.a_sel; const char* cB = (const char*)g.Bt + (size_t)cur.pn * tstep;
;     S.a_ready(cur);
;     if constexpr (SP2) {
;         PG8_STAGE(PG8_SB(0, 0), cB, voffB); PG8_STAGE(PG8_SB(0, 1), cB + hstep, voffB); PG8_STAGE(PG8_SA(0, 0), cA, voffA); PG8_STAGE(PG8_SA(0, 1), cA + hstep, voffA);
;         if (wr == 1) PG8_BAR;
;         PG8_WAIT_V(2); PG8_BAR;
;         PG8_STAGE(PG8_SB(1, 0), cB + kstep, voffB); PG8_STAGE(PG8_SA(1, 0), cA + kstep, voffA); PG8_STAGE(PG8_SB(1, 1), cB + hstep + kstep, voffB);
;         PG8_WAIT_V(6); PG8_BAR;
;     } else {
;         PG8_STAGE(PG8_SB(0, 0), cB, voffB); PG8_STAGE(PG8_SA(0, 0), cA, voffA); PG8_STAGE(PG8_SB(0, 1), cB + hstep, voffB); PG8_STAGE(PG8_SA(0, 1), cA + hstep, voffA);
;         if (wr == 1) PG8_BAR;
;         PG8_WAIT_V(4); PG8_BAR;
.LBB0_172:
	v_writelane_b32 v246, s70, 10
	s_andn2_b64 vcc, exec, s[6:7]
	s_nop 0
	v_writelane_b32 v246, s71, 11
	v_writelane_b32 v246, s72, 12
	s_nop 1
	v_writelane_b32 v246, s73, 13
	s_cbranch_vccnz .LBB0_439
	v_ashrrev_i32_e32 v3, 31, v10
	v_lshrrev_b32_e32 v3, 26, v3
	v_add_u32_e32 v3, v10, v3
	v_ashrrev_i32_e32 v11, 6, v3
	v_bfe_i32 v3, v10, 27, 1
	v_lshlrev_b32_e32 v2, 4, v10
	v_lshrrev_b32_e32 v3, 22, v3
	v_add_u32_e32 v3, v2, v3
	v_and_b32_e32 v3, 0xfffffc00, v3
	v_sub_u32_e32 v3, v2, v3
	v_lshrrev_b32_e32 v4, 4, v3
	v_bitop3_b32 v3, v4, v3, 32 bitop3:0x6c
	v_ashrrev_i32_e32 v5, 31, v3
	v_lshrrev_b32_e32 v5, 26, v5
	v_add_u32_e32 v5, v3, v5
	v_lshlrev_b32_e32 v4, 3, v11
	v_ashrrev_i32_e32 v12, 6, v5
	v_and_b32_e32 v5, 0xc0, v5
	v_and_b32_e32 v4, -16, v4
	v_sub_u32_e32 v3, v3, v5
	v_mov_b32_e32 v5, 1
	v_add_u32_e32 v4, v12, v4
	v_ashrrev_i16_sdwa v3, v5, sext(v3) dst_sel:DWORD dst_unused:UNUSED_PAD src0_sel:DWORD src1_sel:BYTE_0
	v_lshlrev_b32_e32 v6, 5, v11
	v_bfe_i32 v13, v3, 0, 16
	v_lshlrev_b32_e32 v3, 1, v4
	v_lshrrev_b32_e32 v7, 2, v4
	v_and_b32_e32 v8, 3, v12
	s_mov_b32 s5, 0x1fffe0
	v_and_b32_e32 v6, 32, v6
	v_and_b32_e32 v3, 24, v3
	v_and_b32_e32 v7, 4, v7
	v_and_or_b32 v8, v4, s5, v8
	v_or3_b32 v3, v8, v7, v3
	v_add_lshl_u32 v6, v6, v13, 1
	v_add_u32_e32 v2, 0x2000, v2
	v_lshl_add_u32 v148, v3, 11, v6
	v_ashrrev_i32_e32 v3, 31, v2
	v_lshrrev_b32_e32 v3, 22, v3
	v_add_u32_e32 v3, v2, v3
	v_ashrrev_i32_e32 v14, 10, v3
	v_mul_i32_i24_e32 v3, 0x400, v14
	s_mov_b64 s[28:29], s[26:27]
	v_sub_u32_e32 v2, v2, v3
	v_lshrrev_b32_e32 v3, 4, v2
	v_bitop3_b32 v2, v3, v2, 32 bitop3:0x6c
	v_lshl_add_u32 v146, v4, 11, v6
	v_ashrrev_i32_e32 v4, 31, v2
	v_lshrrev_b32_e32 v4, 26, v4
	s_waitcnt lgkmcnt(0)
	s_add_u32 s23, s28, 0x2b00000
	v_add_u32_e32 v4, v2, v4
	s_addc_u32 s61, s29, 0
	v_lshlrev_b32_e32 v3, 3, v14
	v_ashrrev_i32_e32 v15, 6, v4
	v_and_b32_e32 v4, 0xc0, v4
	s_add_u32 s63, s28, 0x800000
	v_and_b32_e32 v3, -16, v3
	v_sub_u32_e32 v2, v2, v4
	s_addc_u32 s65, s29, 0
	s_ashr_i32 s4, s8, 6
	v_add_u32_e32 v3, v15, v3
	v_ashrrev_i16_sdwa v2, v5, sext(v2) dst_sel:DWORD dst_unused:UNUSED_PAD src0_sel:DWORD src1_sel:BYTE_0
	v_and_b32_e32 v5, 3, v15
	s_ashr_i32 s13, s12, 31
	s_ashr_i32 s17, s16, 31
	v_and_or_b32 v5, v3, s5, v5
	s_ashr_i32 s5, s8, 8
	s_lshl_b32 s67, s4, 10
	s_lshl_b64 s[6:7], s[12:13], 19
	s_lshl_b64 s[10:11], s[16:17], 19
	s_add_u32 s14, s63, s10
	v_lshlrev_b32_e32 v6, 5, v14
	v_bfe_i32 v16, v2, 0, 16
	v_lshlrev_b32_e32 v2, 1, v3
	v_lshrrev_b32_e32 v4, 2, v3
	s_addc_u32 s15, s65, s11
	s_add_i32 s69, s67, 0
	v_and_b32_e32 v6, 32, v6
	v_and_b32_e32 v2, 24, v2
	v_and_b32_e32 v4, 4, v4
	s_add_i32 m0, s69, 0x10000
	v_or3_b32 v2, v5, v4, v2
	v_add_lshl_u32 v4, v6, v16, 1
	global_load_lds_dwordx4 v148, s[14:15]
	s_add_i32 m0, s69, 0x12000
	v_lshl_add_u32 v152, v2, 11, v4
	s_add_u32 s10, s14, 0x40000
	global_load_lds_dwordx4 v152, s[14:15]
	s_addc_u32 s11, s15, 0
	s_add_i32 m0, s69, 0x14000
	v_lshl_add_u32 v150, v3, 11, v4
	global_load_lds_dwordx4 v148, s[10:11]
	s_add_i32 m0, s69, 0x16000
	v_mov_b32_e32 v155, 0
	global_load_lds_dwordx4 v152, s[10:11]
	s_add_u32 s10, s23, s6
	s_addc_u32 s11, s61, s7
	s_add_i32 s71, s69, 0x2000
	s_mov_b32 m0, s69
	s_add_u32 s6, s10, 0x40000
	global_load_lds_dwordx4 v146, s[10:11]
	s_mov_b32 m0, s71
	s_addc_u32 s7, s11, 0
	s_add_i32 s73, s69, 0x4000
	global_load_lds_dwordx4 v150, s[10:11]
	s_mov_b32 m0, s73
	s_add_i32 s36, s69, 0x6000
	global_load_lds_dwordx4 v146, s[6:7]
	s_mov_b32 m0, s36
	v_mov_b32_e32 v149, v155
	global_load_lds_dwordx4 v150, s[6:7]
	v_mov_b32_e32 v153, v155
	v_mov_b32_e32 v147, v155
	v_mov_b32_e32 v151, v155
	s_cmp_eq_u32 s5, 1
	s_mov_b32 s31, 0
	v_lshl_add_u64 v[8:9], s[14:15], 0, v[148:149]
	v_lshl_add_u64 v[6:7], s[14:15], 0, v[152:153]
	v_lshl_add_u64 v[2:3], s[10:11], 0, v[146:147]
	s_cselect_b64 s[42:43], -1, 0
	s_cmp_lg_u32 s5, 1
	v_lshl_add_u64 v[4:5], s[10:11], 0, v[150:151]
	s_cbranch_scc1 .LBB0_175
	s_barrier

; #define LAS __attribute__((address_space(3)))
; __device__ __forceinline__ void attn_unit(LAS unsigned char* lds, bf16* Q, const bf16* Kg, const bf16* Vg, const float* snk, int unit, int tid) {
;     const int lane = tid & 63, wave = tid >> 6, fr = lane & 15, fq = lane >> 4;
;     const int b = unit >> 6, n = (unit >> 1) & 31, h = unit & 1, r0 = b * SEQ + n * 128, hq = 8 * h + wave;
;     const v4u zero4 = {0u, 0u, 0u, 0u};
;     bf16* qbase = Q + (size_t)(r0 + fr) * 1024 + hq * 64;
;     bf16x8_t qf[8][2];
; #pragma unroll
;     for (int mt = 0; mt < 8; ++mt) { qf[mt][0] = *(const bf16x8_t*)(qbase + (size_t)mt * 16 * 1024 + 8 * fq); qf[mt][1] = *(const bf16x8_t*)(qbase + (size_t)mt * 16 * 1024 + 32 + 8 * fq); }
; #pragma unroll
;     for (int i = 0; i < 4; ++i) { const int idx = tid + 512 * i, j = idx >> 3, c = idx & 7, p = n * 128 - 128 + j;
;         v4u w = zero4; if (p >= 0) w = *(const v4u*)(Kg + (size_t)(b * SEQ + p) * 128 + h * 64 + c * 8);
;         *(LAS v4u*)(lds + j * ATT_KP + c * 16) = w; }
; #pragma unroll
;     for (int i = 0; i < 2; ++i) { const int idx = tid + 512 * i, j = (idx >> 3) * 2, c = idx & 7, p = n * 128 - 128 + j;
;         v4u w0 = zero4, w1 = zero4;
;         if (p >= 0) { w0 = *(const v4u*)(Vg + (size_t)(b * SEQ + p) * 128 + h * 64 + c * 8); w1 = *(const v4u*)(Vg + (size_t)(b * SEQ + p + 1) * 128 + h * 64 + c * 8); }
;         const unsigned A0[4] = {w0.x, w0.y, w0.z, w0.w}, A1[4] = {w1.x, w1.y, w1.z, w1.w};
; #pragma unroll
;         for (int e = 0; e < 8; ++e) { const unsigned lo = (e & 1) ? (A0[e >> 1] >> 16) : (A0[e >> 1] & 0xffffu), hi = (e & 1) ? (A1[e >> 1] & 0xffff0000u) : (A1[e >> 1] << 16);
;             *(LAS unsigned*)(lds + ATT_VOFF + (8 * c + e) * ATT_VP + j * 2) = lo | hi; } }
;     __syncthreads();
;     const float sink = snk[hq] * 1.4426950408889634f;
;     bool lo_ok[4];
; #pragma unroll
; __global__ void __launch_bounds__(512, 2) fwd_mega(Args a) {
;     ...
;         {
;             int tid_ = threadIdx.x; asm volatile("" : "+v"(tid_));
;             for (int it = bx; it < 512; it += G) {
;                 if (it < 256) attn_unit(lds, WSP(WS_Q), WSP(WS_K), WSP(WS_V), INF(7) + l * 16, it, tid_);
;                 else sgu_unit(lds, WSP(WS_U), WSP(WS_VS), (const float*)(a.ws + WS_SGS), INF(8) + l * 1024, INF(9) + l * 1024, (const v4u*)(a.ws + WS_WF), INF(11) + l * 8 * 128, it - 256, tid_);
;             }
.LBB0_491:
	s_or_b64 exec, exec, s[4:5]
	s_cmpk_lt_i32 s2, 0x200
	s_cselect_b64 s[4:5], -1, 0
	v_mov_b32_e32 v161, v0
	v_writelane_b32 v246, s4, 18
	s_cmpk_gt_i32 s2, 0x1ff
	s_waitcnt lgkmcnt(0)
	s_barrier
	v_writelane_b32 v246, s5, 19
	s_cbranch_scc1 .LBB0_512
	s_mov_b64 s[14:15], s[26:27]
	s_load_dwordx2 s[42:43], s[0:1], 0x58
	v_and_b32_e32 v6, 7, v161
	v_add_u32_e32 v8, 0x200, v161
	v_lshlrev_b32_e32 v170, 3, v6
	v_mul_u32_u24_e32 v10, 0x110, v6
	v_bfe_u32 v15, v161, 4, 2
	v_lshlrev_b32_e32 v4, 4, v6
	s_waitcnt vmcnt(1)
	v_mul_u32_u24_e32 v20, 0x1080, v6
	v_ashrrev_i32_e32 v6, 2, v8
	v_ashrrev_i32_e32 v169, 6, v161
	s_movk_i32 s6, 0x4400
	v_add_u32_e32 v9, 0x400, v161
	v_and_b32_e32 v177, -2, v6
	v_lshlrev_b32_e32 v6, 2, v15
	s_waitcnt lgkmcnt(0)
	s_add_u32 s48, s14, 0x4b00000
	v_and_b32_e32 v3, 63, v161
	v_and_b32_e32 v163, 15, v161
	v_mul_lo_u32 v5, v169, s6
	v_ashrrev_i32_e32 v173, 3, v8
	v_ashrrev_i32_e32 v174, 3, v9
	v_add_u32_e32 v9, 0x600, v161
	v_or_b32_e32 v8, 2, v6
	s_addc_u32 s49, s15, 0
	v_mov_b32_e32 v147, 0
	v_ashrrev_i32_e32 v175, 3, v9
	v_ashrrev_i32_e32 v9, 2, v161
	v_cmp_gt_u32_e64 s[10:11], v8, v163
	v_or_b32_e32 v8, 3, v6
	v_lshlrev_b32_e32 v146, 4, v3
	s_add_u32 s52, s14, 0xf400000
	v_add_u32_e32 v3, 0, v5
	v_lshrrev_b32_e32 v5, 1, v161
	v_bfe_u32 v2, v161, 3, 3
	v_and_b32_e32 v176, -2, v9
	v_cmp_gt_u32_e64 s[12:13], v8, v163
	v_lshl_add_u64 v[8:9], s[14:15], 0, v[146:147]
	s_mov_b64 s[16:17], 0x680000
	s_addc_u32 s53, s15, 0
	v_and_b32_e32 v146, 24, v5
	v_lshlrev_b32_e32 v167, 3, v161
	v_lshlrev_b32_e32 v7, 11, v2
	v_lshlrev_b32_e32 v11, 2, v2
	v_lshlrev_b32_e32 v12, 4, v2
	v_bfe_u32 v2, v161, 3, 1
	v_lshl_add_u64 v[148:149], v[8:9], 0, s[16:17]
	v_lshl_add_u64 v[8:9], s[14:15], 0, v[146:147]
	s_mov_b64 s[16:17], 0x9300000
	s_add_u32 s56, s14, 0x6b00000
	v_mov_b32_e32 v5, v147
	v_and_or_b32 v2, v167, 56, v2
	s_load_dwordx4 s[28:31], s[0:1], 0x38
	s_load_dwordx2 s[50:51], s[0:1], 0x48
	v_lshl_add_u64 v[150:151], v[8:9], 0, s[16:17]
	s_addc_u32 s57, s15, 0
	v_add_u32_e32 v8, 0, v4
	v_lshl_add_u64 v[4:5], s[14:15], 0, v[4:5]
	s_mov_b64 s[14:15], 0x8b00000
	v_mul_u32_u24_e32 v14, 0x110, v2
	v_lshlrev_b32_e32 v2, 3, v15
	v_lshl_add_u64 v[152:153], v[4:5], 0, s[14:15]
	s_mov_b64 s[14:15], 0x8f00000
	v_lshl_add_u32 v9, v15, 4, 0
	v_and_b32_e32 v13, 48, v161
	v_ashrrev_i32_e32 v171, 3, v161
	s_movk_i32 s18, 0x90
	v_add3_u32 v178, v3, v10, v11
	v_lshl_add_u64 v[154:155], v[4:5], 0, s[14:15]
	v_sub_u32_e32 v10, v9, v2
	s_movk_i32 s14, 0x210
	s_movk_i32 s4, 0x80
	v_mul_lo_u32 v16, v171, s18
	v_mul_lo_u32 v17, v173, s18
	v_mul_lo_u32 v18, v174, s18
	v_mul_lo_u32 v19, v175, s18
	v_add_u32_e32 v3, v3, v13
	v_lshl_add_u32 v4, v176, 1, 0
	v_lshl_add_u32 v5, v177, 1, 0
	v_mad_u32_u24 v180, v163, s14, v10
	s_lshl_b32 s14, s2, 2
	v_ashrrev_i32_e32 v165, 7, v161
	v_cmp_gt_i32_e64 s[4:5], s4, v161
	v_and_b32_e32 v168, 64, v161
	v_cmp_gt_u32_e64 s[6:7], v6, v163
	v_cmp_lt_u32_e64 s[8:9], v6, v163
	s_mov_b32 s55, 0
	v_mad_u32_u24 v179, v163, s18, v9
	s_add_i32 s23, s14, 0xfffffc00
	s_lshl_b32 s24, s3, 2
	s_lshl_b32 s25, s2, 6
	s_lshl_b32 s34, s3, 6
	s_movk_i32 s35, 0x1000
	s_movk_i32 s36, 0x2000
	s_movk_i32 s37, 0x3000
	s_movk_i32 s38, 0x4000
	s_mov_b32 s58, 0x3a800000
	s_mov_b32 s39, 0x800000
	v_lshlrev_b32_e32 v181, 1, v7
	s_mov_b32 s40, 0x8000
	s_mov_b32 s41, 0x10000
	s_mov_b32 s44, 0x18000
	s_mov_b32 s45, 0x20000
	s_mov_b32 s46, 0x28000
	s_mov_b32 s47, 0x30000
	s_mov_b32 s59, 0x38000
	v_add_u32_e32 v182, 0, v12
	s_mov_b32 s60, 0xffff0000
	v_add_u32_e32 v183, v3, v14
	v_lshlrev_b32_e32 v146, 1, v2
	v_add_u32_e32 v184, v8, v16
	v_add_u32_e32 v185, v8, v17
	v_add_u32_e32 v186, v8, v18
	v_add_u32_e32 v187, v8, v19
	s_mov_b32 s61, 0xffff
	v_add_u32_e32 v188, v4, v20
	v_add_u32_e32 v189, v5, v20
	s_mov_b32 s62, 0x3fb8aa3b
	v_lshlrev_b32_e32 v156, 1, v6
	v_mbcnt_hi_u32_b32 v190, -1, v1
	v_mov_b32_e32 v191, 0xff800000
	s_mov_b32 s63, s2
	s_branch .LBB0_495

;     __host__ __device__ void init(int M, int N, int G_, int c_) { base.init(M, N, G_, c_); G = G_; c = c_; }
;     __host__ __device__ void init(int M, int G_, int c_) { base.init(M, 1024, G_, c_); }
;     __host__ __device__ bool next(int i, Unit& u) const { Unit b; if (!base.next(i >> 1, b)) return false; u.pm = b.pm; u.pn = b.pn + 4 * (i & 1); return true; }
;     __host__ __device__ bool next(int i, Unit& u) const {
;         const long L = (long)i * G + c; if (L >= nwg) return false;
;         int wgid = (int)L; { const int q = nwg / NXCD, r = nwg % NXCD, xcd = wgid % NXCD, off = wgid / NXCD; wgid = (xcd < r ? xcd * (q + 1) : r * (q + 1) + (xcd - r) * q) + off; }
;         const int nig = WGM * nN, gid = wgid / nig, fm = gid * WGM, gsz = (nM - fm) < WGM ? (nM - fm) : WGM;
;         u.pm = fm + ((wgid % nig) % gsz); u.pn = (wgid % nig) / gsz; return true;
;     }
; __global__ void __launch_bounds__(512, 2) fwd_mega(Args a) {
;     ...
;             pg8::Gemm g{WSP(WS_Q), WSP(WS_PAB), M, 2048, D, 4, (size_t)(WS_U - WS_Q)}; pg8::PairOrder S; S.init(M, G, bx);
;             pg8::EpiMerge E{WSP(WS_MG), WSP(WS_GA), WSP(WS_GB)};
;             pg8::gemm_phase<pg8::EpiMerge, pg8::PairOrder, true, true, true>(lds, g, S, E);
.LBB0_564:
	s_or_b64 exec, exec, s[4:5]
	s_waitcnt lgkmcnt(0)
	s_barrier
	s_mov_b64 s[6:7], s[26:27]
	v_mov_b32_e32 v10, v0
	s_cmpk_lt_i32 s2, 0x100
	s_cselect_b64 s[8:9], -1, 0
	s_cmpk_gt_i32 s2, 0xff
	v_readfirstlane_b32 s20, v10
	s_cbranch_scc1 .LBB0_570
	s_ashr_i32 s4, s2, 31
	s_lshr_b32 s4, s4, 29
	s_add_i32 s10, s2, s4
	s_and_b32 s4, s10, -8
	s_sub_i32 s11, s2, s4
	s_cmp_gt_i32 s11, -1
	s_cbranch_scc0 .LBB0_567
	s_lshl_b32 s12, s11, 5
	s_cbranch_execz .LBB0_568
	s_branch .LBB0_569

;     __host__ __device__ void init(int M, int N, int G_, int c_) { base.init(M, N, G_, c_); G = G_; c = c_; }
;     __host__ __device__ void init(int M, int G_, int c_) { base.init(M, 1024, G_, c_); }
;     __host__ __device__ bool next(int i, Unit& u) const { Unit b; if (!base.next(i >> 1, b)) return false; u.pm = b.pm; u.pn = b.pn + 4 * (i & 1); return true; }
;     __host__ __device__ bool next(int i, Unit& u) const {
;         const long L = (long)i * G + c; if (L >= nwg) return false;
;         int wgid = (int)L; { const int q = nwg / NXCD, r = nwg % NXCD, xcd = wgid % NXCD, off = wgid / NXCD; wgid = (xcd < r ? xcd * (q + 1) : r * (q + 1) + (xcd - r) * q) + off; }
;         const int nig = WGM * nN, gid = wgid / nig, fm = gid * WGM, gsz = (nM - fm) < WGM ? (nM - fm) : WGM;
;         u.pm = fm + ((wgid % nig) % gsz); u.pn = (wgid % nig) / gsz; return true;
;     }
; __global__ void __launch_bounds__(512, 2) fwd_mega(Args a) {
;     ...
;         {
;             pg8::Gemm g{WSP(WS_MG), WSP(WS_WO2), M, D, D, 1 << 20, 0}; pg8::StaticOrder S; S.init(M, D, G, bx);
;             const float* ml = (const float*)(a.ws + WS_MOD) + (size_t)l * 4 * 6144;
;     ...
;             if constexpr (l == 0) {
;                 pg8::EpiResidNorm<false, false> E{INF(0), WSP(WS_XMID), ml + 2048, WSP(WS_H2), INF(15) + l * D, ml, 3072, 4096, st};
;                 pg8::gemm_phase<pg8::EpiResidNorm<false, false>, pg8::StaticOrder, false, true>(lds, g, S, E);
.LBB0_710:
	s_or_b64 exec, exec, s[6:7]
	v_mov_b32_e32 v166, v0
	s_waitcnt lgkmcnt(0)
	s_barrier
	s_and_b64 vcc, exec, s[74:75]
	v_readfirstlane_b32 s4, v166
	s_cbranch_vccnz .LBB0_773
	s_ashr_i32 s24, s2, 31
	s_mov_b64 s[12:13], s[26:27]
	s_lshr_b32 s5, s24, 29
	s_add_i32 s8, s2, s5
	s_and_b32 s5, s8, -8
	s_sub_i32 s9, s2, s5
	s_cmp_gt_i32 s9, -1
	s_cbranch_scc0 .LBB0_713
	s_lshl_b32 s5, s9, 5
	s_cbranch_execz .LBB0_714
	s_branch .LBB0_715

; #define PG8_BAR __builtin_amdgcn_s_barrier()
; template <class Epi, class Sched, bool ALIGN_EPI = false, bool SP2 = false, bool PAIR_ACC = false>
; __device__ __forceinline__ void gemm_phase(PG8_LAS unsigned char* lds, const Gemm g, const Sched& S, const Epi& E) {
;     ...
;     const int tid = tid_, wid = __builtin_amdgcn_readfirstlane(tid >> 6), lane = tid & 63, wr = wid >> 2, wc = wid & 3, fr = lane & 15, fq = lane >> 4;
;     const int K = g.K, nt = K / BK;
;     unsigned voffA[2], voffB[2];
; #pragma unroll
;     for (int i = 0; i < 2; ++i) { int R, C; stage_rc(tid * 16 + i * 8192, R, C); const int Rb = Epi::PERM ? ((R & ~31) + perm32(R & 31)) : R;
;         voffA[i] = (unsigned)(R * K + C) * 2u; voffB[i] = (unsigned)(Rb * K + C) * 2u; }
;     const size_t kstep = (size_t)(BK * 2);
;     const size_t hstep = (size_t)HALF * K * 2;
;     const size_t tstep = 2 * hstep;
;     const unsigned ldsw = (unsigned)wid * 1024u;
;     const int aoff = lds_byte(wr * 64 + fr, fq * 8), boff = lds_byte(wc * 32 + fr, fq * 8);
;     ...
;     Unit cur, nxt; int ui = 0;
;     if (!S.next(0, cur)) return;
;     f32x4 acc[2][2][4][2];
; #pragma unroll
;     for (int a = 0; a < 2; ++a)
; #pragma unroll
;         for (int b = 0; b < 2; ++b)
; #pragma unroll
;             for (int m = 0; m < 4; ++m)
; #pragma unroll
;                 for (int n = 0; n < 2; ++n) acc[a][b][m][n] = (f32x4){0.f, 0.f, 0.f, 0.f};
;     bf16x8 At[4][2], B0[2][2], B1[2][2];
;     const char* cA = (const char*)g.A + (size_t)cur.pm * tstep + (size_t)(cur.pn / g.a_div) * g.a_sel; const char* cB = (const char*)g.Bt + (size_t)cur.pn * tstep;
;     S.a_ready(cur);
;     if constexpr (SP2) {
;         PG8_STAGE(PG8_SB(0, 0), cB, voffB); PG8_STAGE(PG8_SB(0, 1), cB + hstep, voffB); PG8_STAGE(PG8_SA(0, 0), cA, voffA); PG8_STAGE(PG8_SA(0, 1), cA + hstep, voffA);
;         if (wr == 1) PG8_BAR;
;         PG8_WAIT_V(2); PG8_BAR;
; __global__ void __launch_bounds__(512, 2) fwd_mega(Args a) {
;     ...
;         {
;             pg8::Gemm g{WSP(WS_H2), WSP(WS_WGU), M, 2 * FF, D, 1 << 20, 0}; pg8::StaticOrder S; S.init(M, 2 * FF, G, bx);
;             pg8::EpiGUConv E{WSP(WS_ACT), (float*)(a.ws + WS_RAWA), (float*)(a.ws + WS_RAWU), (float*)(a.ws + WS_TAILA), INF(18) + (size_t)l * 3 * FF, INF(19) + (size_t)l * FF, lds + XCH_OFF};
;             pg8::gemm_phase<pg8::EpiGUConv, pg8::StaticOrder, true, true>(lds, g, S, E);
.LBB0_825:
	s_or_b64 exec, exec, s[6:7]
	s_cmpk_lt_i32 s2, 0x580
	s_cselect_b64 s[4:5], -1, 0
	v_writelane_b32 v246, s4, 16
	v_mov_b32_e32 v13, v0
	s_waitcnt lgkmcnt(0)
	v_writelane_b32 v246, s5, 17
	s_barrier
	s_cmpk_gt_i32 s2, 0x57f
	v_readfirstlane_b32 s9, v13
	v_writelane_b32 v246, s74, 14
	s_nop 1
	v_writelane_b32 v246, s75, 15
	s_cbranch_scc1 .LBB0_850
	v_lshlrev_b32_e32 v2, 4, v13
	v_add_u32_e32 v3, 0x2000, v2
	v_ashrrev_i32_e32 v4, 31, v3
	v_lshrrev_b32_e32 v4, 22, v4
	v_add_u32_e32 v4, v3, v4
	v_ashrrev_i32_e32 v10, 10, v4
	v_mul_i32_i24_e32 v4, 0x400, v10
	v_sub_u32_e32 v3, v3, v4
	v_lshrrev_b32_e32 v4, 4, v3
	v_bitop3_b32 v3, v4, v3, 32 bitop3:0x6c
	v_ashrrev_i32_e32 v4, 31, v3
	v_lshrrev_b32_e32 v4, 26, v4
	v_add_u32_e32 v4, v3, v4
	v_lshlrev_b32_e32 v5, 3, v10
	v_ashrrev_i32_e32 v11, 6, v4
	v_and_b32_e32 v5, -16, v5
	v_add_u32_e32 v5, v11, v5
	v_and_b32_e32 v6, 3, v11
	s_mov_b32 s8, 0x1fffe0
	v_lshrrev_b32_e32 v7, 2, v5
	v_lshlrev_b32_e32 v8, 1, v5
	v_and_b32_e32 v4, 0xc0, v4
	v_and_or_b32 v6, v5, s8, v6
	v_and_b32_e32 v7, 4, v7
	v_and_b32_e32 v8, 24, v8
	v_sub_u32_e32 v3, v3, v4
	v_mov_b32_e32 v4, 1
	v_or3_b32 v6, v6, v7, v8
	v_lshlrev_b32_e32 v7, 5, v10
	v_ashrrev_i16_sdwa v3, v4, sext(v3) dst_sel:DWORD dst_unused:UNUSED_PAD src0_sel:DWORD src1_sel:BYTE_0
	v_and_b32_e32 v7, 32, v7
	v_bfe_i32 v12, v3, 0, 16
	v_add_lshl_u32 v3, v7, v12, 1
	v_lshl_add_u32 v174, v6, 11, v3
	v_lshl_add_u32 v176, v5, 11, v3
	v_bfe_i32 v3, v13, 27, 1
	v_lshrrev_b32_e32 v3, 22, v3
	v_add_u32_e32 v3, v2, v3
	s_mov_b64 s[6:7], s[26:27]
	v_and_b32_e32 v3, 0xfffffc00, v3
	v_sub_u32_e32 v2, v2, v3
	v_lshrrev_b32_e32 v3, 4, v2
	v_ashrrev_i32_e32 v5, 31, v13
	v_bitop3_b32 v2, v3, v2, 32 bitop3:0x6c
	v_lshrrev_b32_e32 v5, 26, v5
	v_ashrrev_i32_e32 v3, 31, v2
	v_add_u32_e32 v5, v13, v5
	s_waitcnt lgkmcnt(0)
	s_add_u32 s4, s6, 0x4b00000
	v_lshrrev_b32_e32 v3, 26, v3
	v_ashrrev_i32_e32 v15, 6, v5
	s_addc_u32 s5, s7, 0
	v_add_u32_e32 v3, v2, v3
	v_lshlrev_b32_e32 v5, 3, v15
	s_add_u32 s23, s6, 0x1a80000
	v_ashrrev_i32_e32 v14, 6, v3
	v_and_b32_e32 v5, -16, v5
	s_addc_u32 s24, s7, 0
	v_add_u32_e32 v5, v14, v5
	v_and_b32_e32 v6, 3, v14
	s_ashr_i32 s34, s2, 31
	v_and_or_b32 v6, v5, s8, v6
	s_lshr_b32 s8, s34, 29
	s_add_i32 s8, s2, s8
	s_ashr_i32 s41, s9, 6
	s_ashr_i32 s10, s8, 3
	s_and_b32 s8, s8, -8
	s_ashr_i32 s40, s9, 8
	s_lshl_b32 s25, s41, 10
	s_sub_i32 s8, s2, s8
	s_cmp_lt_i32 s8, 0
	s_movk_i32 s35, 0xb1
	s_cselect_b32 s11, s35, 0xb0
	s_mul_i32 s8, s11, s8
	s_add_i32 s8, s8, s10
	s_mul_hi_i32 s10, s8, 0x2e8ba2e9
	s_lshr_b32 s11, s10, 31
	s_ashr_i32 s10, s10, 5
	s_add_i32 s10, s10, s11
	s_lshl_b32 s11, s10, 3
	s_mulk_i32 s10, 0xb0
	s_sub_i32 s10, s8, s10
	s_sext_i32_i16 s8, s10
	s_bfe_u32 s8, s8, 0x3001c
	s_add_i32 s12, s10, s8
	s_sext_i32_i16 s8, s12
	s_and_b32 s12, s12, 0xfff8
	s_sub_i32 s10, s10, s12
	s_sext_i32_i16 s10, s10
	v_lshrrev_b32_e32 v7, 2, v5
	v_lshlrev_b32_e32 v8, 1, v5
	v_and_b32_e32 v3, 0xc0, v3
	s_lshr_b32 s8, s8, 3
	s_add_i32 s70, s11, s10
	v_and_b32_e32 v7, 4, v7
	v_and_b32_e32 v8, 24, v8
	v_sub_u32_e32 v2, v2, v3
	s_ashr_i32 s71, s70, 31
	s_bfe_i64 s[12:13], s[8:9], 0x100000
	v_or3_b32 v6, v6, v7, v8
	v_lshlrev_b32_e32 v7, 5, v15
	v_ashrrev_i16_sdwa v2, v4, sext(v2) dst_sel:DWORD dst_unused:UNUSED_PAD src0_sel:DWORD src1_sel:BYTE_0
	s_lshl_b64 s[10:11], s[70:71], 19
	s_lshl_b64 s[12:13], s[12:13], 19
	v_and_b32_e32 v7, 32, v7
	v_bfe_i32 v16, v2, 0, 16
	s_add_u32 s38, s23, s12
	v_add_lshl_u32 v2, v7, v16, 1
	s_addc_u32 s39, s24, s13
	s_add_i32 s36, s25, 0
	v_lshl_add_u32 v178, v6, 11, v2
	s_add_i32 m0, s36, 0x10000
	v_lshl_add_u32 v180, v5, 11, v2
	global_load_lds_dwordx4 v178, s[38:39]
	s_add_i32 m0, s36, 0x12000
	s_add_u32 s12, s38, 0x40000
	global_load_lds_dwordx4 v174, s[38:39]
	s_addc_u32 s13, s39, 0
	s_add_i32 m0, s36, 0x14000
	v_mov_b32_e32 v179, 0
	global_load_lds_dwordx4 v178, s[12:13]
	s_add_i32 m0, s36, 0x16000
	s_add_u32 s10, s4, s10
	s_addc_u32 s11, s5, s11
	s_add_i32 s37, s36, 0x2000
	global_load_lds_dwordx4 v174, s[12:13]
	s_mov_b32 m0, s36
	s_add_u32 s12, s10, 0x40000
	global_load_lds_dwordx4 v180, s[10:11]
	s_mov_b32 m0, s37
	s_addc_u32 s13, s11, 0
	s_add_i32 s42, s36, 0x4000
	global_load_lds_dwordx4 v176, s[10:11]
	s_mov_b32 m0, s42
	s_add_i32 s43, s36, 0x6000
	global_load_lds_dwordx4 v180, s[12:13]
	s_mov_b32 m0, s43
	v_mov_b32_e32 v175, v179
	global_load_lds_dwordx4 v176, s[12:13]
	s_load_dwordx4 s[12:15], s[0:1], 0x90
	v_mov_b32_e32 v181, v179
	v_mov_b32_e32 v177, v179
	s_cmp_eq_u32 s40, 1
	s_mov_b32 s44, 0
	v_lshl_add_u64 v[8:9], s[38:39], 0, v[178:179]
	v_lshl_add_u64 v[6:7], s[38:39], 0, v[174:175]
	v_lshl_add_u64 v[2:3], s[10:11], 0, v[180:181]
	s_cselect_b64 s[16:17], -1, 0
	s_cmp_lg_u32 s40, 1
	v_lshl_add_u64 v[4:5], s[10:11], 0, v[176:177]
	s_cbranch_scc1 .LBB0_828
	s_barrier

; __device__ __forceinline__ float sigm(float v) { return __builtin_amdgcn_rcpf(1.0f + __expf(-v)); }
;     __host__ __device__ void init(int M, int N, int G_, int c_) { base.init(M, N, G_, c_); G = G_; c = c_; }
;     __host__ __device__ void init(int M, int G_, int c_) { base.init(M, 1024, G_, c_); }
;     __host__ __device__ bool next(int i, Unit& u) const { Unit b; if (!base.next(i >> 1, b)) return false; u.pm = b.pm; u.pn = b.pn + 4 * (i & 1); return true; }
; __device__ __forceinline__ unsigned f2bf(float f) { unsigned u = __builtin_bit_cast(unsigned, f); return (u + 0x7fffu + ((u >> 16) & 1u)) >> 16; }
; __global__ void __launch_bounds__(512, 2) fwd_mega(Args a) {
;     ...
;         {
;             pg8::Gemm g{WSP(WS_ACT), WSP(l == 0 ? WS_WD : WS_WD1), M, D, FF, 1 << 20, 0}; pg8::StaticOrder S; S.init(M, D, G, bx);
;             {
;                 const float* cw = INF(18) + (size_t)l * 3 * FF; const float* cbp = INF(19) + (size_t)l * FF;
;                 const float* RA = (const float*)(a.ws + WS_RAWA); const float* RU = (const float*)(a.ws + WS_RAWU); const float* TA = (const float*)(a.ws + WS_TAILA);
;                 pg8::Unit fu;
;                 for (int i = 0; S.next(i, fu); ++i) {
;                     if ((fu.pm & 15) == 0) continue;
;                     for (int idx = threadIdx.x; idx < 2 * FF; idx += 512) {
;                         const int j = idx / FF, f = idx % FF; const size_t cur = (size_t)fu.pm * 2 * FF, prv = (size_t)(fu.pm - 1) * 2 * FF;
;                         const float a2 = RA[cur + j * FF + f], a1 = (j == 0) ? TA[prv + FF + f] : RA[cur + f], a0 = (j == 0) ? TA[prv + f] : TA[prv + FF + f];
;                         const float cv = cbp[f] + cw[f] * a0 + cw[FF + f] * a1 + cw[2 * FF + f] * a2;
;                         WSP(WS_ACT)[(size_t)(fu.pm * 256 + j) * FF + f] = (bf16)f2bf(cv * pg8::sigm(cv) * RU[cur + j * FF + f]);
;                     }
;                 }
;                 asm volatile("s_waitcnt vmcnt(0)" ::: "memory"); __syncthreads();
.LBB0_902:
	s_or_b64 exec, exec, s[6:7]
	s_waitcnt lgkmcnt(0)
	s_barrier
	s_mov_b64 s[12:13], s[26:27]
	s_load_dwordx4 s[8:11], s[0:1], 0x90
	s_mov_b32 s23, 0
	v_mov_b64_e32 v[2:3], 0x100
	v_mov_b64_e32 v[4:5], 0xff
	s_waitcnt lgkmcnt(0)
	s_add_u32 s20, s12, 0x6b00000
	s_addc_u32 s21, s13, 0
	s_add_u32 s14, s12, 0x200000
	s_addc_u32 s15, s13, 0
	s_add_u32 s16, s12, 0x380000
	s_addc_u32 s17, s13, 0
	s_add_u32 s4, s12, 0x500000
	s_addc_u32 s5, s13, 0
	s_ashr_i32 s67, s3, 31
	s_ashr_i32 s65, s2, 31
	s_movk_i32 s24, 0x1600
	s_movk_i32 s25, 0xaff
	v_mov_b32_e32 v7, 0
	s_movk_i32 s30, 0x2000
	s_movk_i32 s31, 0x5000
	s_movk_i32 s34, 0x7fff
	s_movk_i32 s35, 0x13ff
	v_mov_b32_e32 v10, 0xb00
	v_mov_b64_e32 v[8:9], s[20:21]
	s_branch .LBB0_905

; #define LAS __attribute__((address_space(3)))
; __global__ void __launch_bounds__(512, 2) fwd_mega(Args a) {
;     ...
;     auto convert_items = [&](int LL, int lo, int hi, int w0, int nw_, size_t wd_off) __attribute__((always_inline)) {
;         LAS float* scr = (LAS float*)(lds + wave * 16384);
;         for (int it0 = lo + w0; it0 < hi; it0 += nw_) {
;             int it = it0;
;             if (it < 2688) { const int kb = it / 168, nb = it % 168; tr_item(INF(6) + (size_t)LL * D * INC, INC, WSP(WS_WIN), 1024, 0, 32 * nb, 64 * kb, 32 * nb, scr, lane); continue; } it -= 2688;
;             if (it < 512) { const int kb = it / 32, nb = it % 32; tr_item(INF(13) + (size_t)LL * D * D, D, WSP(WS_PAB), 1024, 0, 32 * nb, 64 * kb, 32 * nb, scr, lane); continue; } it -= 512;
;             if (it < 512) { const int kb = it / 32, nb = it % 32; tr_item(INF(12) + (size_t)LL * D * D, D, WSP(WS_PAB), 1024, 0, 1024 + 32 * nb, 64 * kb, 32 * nb, scr, lane); continue; } it -= 512;
;             if (it < 512) { const int kb = it / 32, nb = it % 32; tr_item(INF(14) + (size_t)LL * D * D, D, WSP(WS_WO2), 1024, 0, 32 * nb, 64 * kb, 32 * nb, scr, lane); continue; } it -= 512;
;             if (it < 1408) { const int kb = it / 88, nb = it % 88, n0 = 32 * nb; tr_item(INF(16) + (size_t)LL * D * FF, FF, WSP(WS_WGU), 1024, 0, (n0 >> 7) * 256 + (n0 & 127), 64 * kb, n0, scr, lane); continue; } it -= 1408;
;             if (it < 1408) { const int kb = it / 88, nb = it % 88, n0 = 32 * nb; tr_item(INF(17) + (size_t)LL * D * FF, FF, WSP(WS_WGU), 1024, 0, (n0 >> 7) * 256 + 128 + (n0 & 127), 64 * kb, n0, scr, lane); continue; } it -= 1408;
;             { const int kb = it / 32, nb = it % 32; tr_item(INF(20) + (size_t)LL * FF * D, D, WSP(wd_off), 2816, 0, 32 * nb, 64 * kb, 32 * nb, scr, lane); }
;         }
;     };
;     ...
;         if constexpr (l + 1 < NL) {
;             __syncthreads();
;             convert_items(l + 1, 0, 8448, gw, NGW, WS_WD1);
;             for (int it = gw; it < 160; it += NGW) sgu_wfrag_item(INF(10) + (size_t)(l + 1) * 8 * 128 * 128, (v4u*)(a.ws + WS_WF), it, lane);
.LBB0_983:
	v_readlane_b32 s4, v246, 4
	v_readlane_b32 s5, v246, 5
	s_andn2_b64 vcc, exec, s[4:5]
	s_barrier
	s_cbranch_vccnz .LBB0_1010
	s_load_dwordx2 s[4:5], s[0:1], 0xa0
	s_mov_b64 s[6:7], s[26:27]
	v_lshlrev_b32_e32 v2, 2, v205
	v_mul_u32_u24_e32 v6, 0x84, v200
	v_readlane_b32 s10, v246, 3
	v_mov_b32_e32 v3, 0
	v_mov_b32_e32 v7, v3
	v_add3_u32 v28, s10, v2, v6
	v_and_b32_e32 v6, 56, v204
	v_mul_u32_u24_e32 v8, 0x84, v6
	v_lshlrev_b32_e32 v6, 1, v6
	s_waitcnt lgkmcnt(0)
	v_lshl_add_u64 v[4:5], s[4:5], 0, v[2:3]
	v_lshl_add_u64 v[26:27], s[6:7], 0, v[6:7]
	s_mov_b64 s[4:5], 0xf600000
	v_lshl_add_u64 v[6:7], v[26:27], 0, s[4:5]
	s_load_dwordx4 s[4:7], s[0:1], 0x80
	v_lshlrev_b32_e32 v9, 2, v201
	s_mov_b64 s[8:9], 0xb00000
	v_add3_u32 v29, s10, v8, v9
	s_load_dwordx2 s[10:11], s[0:1], 0x70
	s_waitcnt lgkmcnt(0)
	v_lshl_add_u64 v[8:9], s[6:7], 0, v[2:3]
	s_mov_b64 s[6:7], 0x1a80000
	v_lshl_add_u64 v[12:13], s[4:5], 0, v[2:3]
	v_lshl_add_u64 v[4:5], v[4:5], 0, s[8:9]
	v_lshl_add_u64 v[8:9], v[8:9], 0, s[8:9]
	v_lshl_add_u64 v[10:11], v[26:27], 0, s[6:7]
	v_lshl_add_u64 v[12:13], v[12:13], 0, s[8:9]
	s_load_dwordx2 s[8:9], s[0:1], 0x30
	s_load_dwordx4 s[4:7], s[0:1], 0x60
	v_lshl_add_u64 v[14:15], s[10:11], 0, v[2:3]
	s_mov_b64 s[10:11], 0x400000
	s_mov_b64 s[12:13], 0x1680000
	s_waitcnt vmcnt(3) lgkmcnt(0)
	v_lshl_add_u64 v[24:25], s[8:9], 0, v[2:3]
	s_waitcnt vmcnt(1)
	v_lshl_add_u64 v[18:19], s[4:5], 0, v[2:3]
	s_mov_b64 s[4:5], 0x1280000
	v_lshl_add_u64 v[20:21], v[26:27], 0, s[4:5]
	s_mov_b64 s[4:5], 0x1500000
	v_lshl_add_u64 v[22:23], s[6:7], 0, v[2:3]
	v_lshl_add_u64 v[24:25], v[24:25], 0, s[4:5]
	s_mov_b64 s[4:5], 0x800000
	v_or_b32_e32 v30, 8, v201
	v_or_b32_e32 v31, 16, v201
	v_or_b32_e32 v32, 24, v201
	v_lshl_add_u64 v[14:15], v[14:15], 0, s[10:11]
	v_lshl_add_u64 v[16:17], v[26:27], 0, s[12:13]
	v_lshl_add_u64 v[18:19], v[18:19], 0, s[10:11]
	v_lshl_add_u64 v[22:23], v[22:23], 0, s[10:11]
	v_lshl_add_u64 v[26:27], v[26:27], 0, s[4:5]
	s_lshl_b32 s4, s22, 5
	s_lshl_b32 s5, s77, 5
	s_lshl_b32 s12, s22, 1
	s_lshl_b32 s13, s77, 1
	s_mov_b32 s7, 0
	s_movk_i32 s14, 0x7fff
	s_mov_b32 s15, 0xffff0000
	s_movk_i32 s16, 0x5000
	s_mov_b32 s17, 0xb000
	s_mov_b32 s18, 0x10000
	s_mov_b32 s19, 0x16000
	s_mov_b32 s20, 0x1b000
	s_mov_b32 s21, 0x21000
	s_mov_b32 s23, 0x26000
	s_mov_b32 s24, 0x2c000
	s_mov_b32 s25, 0x31000
	s_mov_b32 s28, 0x37000
	s_mov_b32 s29, 0x3c000
	s_mov_b32 s30, 0x42000
	s_mov_b32 s31, 0x47000
	s_mov_b32 s34, 0x4d000
	s_mov_b32 s35, 0x52000
	s_mov_b32 s36, 0x58000
	s_mov_b32 s37, 0x5d000
	s_mov_b32 s38, 0x63000
	s_mov_b32 s39, 0x68000
	s_mov_b32 s40, 0x6e000
	s_mov_b32 s41, 0x73000
	s_mov_b32 s42, 0x79000
	s_mov_b32 s43, 0x7e000
	s_mov_b32 s44, 0x84000
	s_mov_b32 s45, 0x89000
	s_mov_b32 s46, 0x8f000
	s_mov_b32 s47, 0x94000
	s_mov_b32 s48, 0x9a000
	s_mov_b32 s49, 0x9f000
	s_mov_b32 s50, 0xa5000
	s_mov_b32 s51, 0xaa000
	s_movk_i32 s52, 0x5400
	v_add_u32_e32 v33, 0x400, v28
	v_add_u32_e32 v34, 0x800, v28
	v_add_u32_e32 v35, 0xc00, v28
	v_add_u32_e32 v36, 0x1000, v28
	v_add_u32_e32 v37, 0x1400, v28
	v_add_u32_e32 v38, 0x1800, v28
	v_add_u32_e32 v39, 0x1c00, v28
	s_mov_b32 s53, s22
	s_branch .LBB0_986

; __device__ __forceinline__ unsigned cvt_pk_bf16(float lo, float hi) { unsigned r; asm volatile("v_cvt_pk_bf16_f32 %0, %1, %2" : "=v"(r) : "v"(lo), "v"(hi)); return r; }
; __device__ __forceinline__ void sgu_wfrag_item(const float* Wl, v4u* WF, int item, int lane) {
;     const int g = item / 20, q = item % 20, fr = lane & 15, fq = lane >> 4;
;     int mt = 0, ks = 0, c = 0;
;     for (int m = 0; m < 8; ++m) for (int k = 0; k <= (m >> 1); ++k) { if (c == q) { mt = m; ks = k; } ++c; }
;     const int t = 16 * mt + fr, sb = 32 * ks + 8 * fq;
;     const float* p = Wl + ((size_t)g * 128 + t) * 128 + sb;
;     const f32x4 wa = *(const f32x4*)p, wb = *(const f32x4*)(p + 4);
;     v4u ww;
;     ww.x = cvt_pk_bf16(sb + 0 <= t ? wa.x : 0.f, sb + 1 <= t ? wa.y : 0.f); ww.y = cvt_pk_bf16(sb + 2 <= t ? wa.z : 0.f, sb + 3 <= t ? wa.w : 0.f);
;     ww.z = cvt_pk_bf16(sb + 4 <= t ? wb.x : 0.f, sb + 5 <= t ? wb.y : 0.f); ww.w = cvt_pk_bf16(sb + 6 <= t ? wb.z : 0.f, sb + 7 <= t ? wb.w : 0.f);
;     WF[(size_t)item * 64 + lane] = ww;
; }
; __global__ void __launch_bounds__(512, 2) fwd_mega(Args a) {
;     ...
;             for (int it = gw; it < 160; it += NGW) sgu_wfrag_item(INF(10) + (size_t)(l + 1) * 8 * 128 * 128, (v4u*)(a.ws + WS_WF), it, lane);
.LBB0_1010:
	v_readlane_b32 s4, v246, 6
	v_readlane_b32 s5, v246, 7
	s_andn2_b64 vcc, exec, s[4:5]
	s_cbranch_vccnz .LBB0_1013
	s_load_dwordx2 s[4:5], s[0:1], 0x50
	s_mov_b64 s[6:7], s[26:27]
	v_mov_b32_e32 v173, 0
	v_and_b32_e32 v4, 24, v203
	s_waitcnt lgkmcnt(0)
	s_add_u32 s4, s4, 0x80000
	v_lshl_add_u64 v[2:3], s[6:7], 0, v[172:173]
	s_mov_b64 s[6:7], 0x680000
	s_addc_u32 s5, s5, 0
	v_lshl_add_u64 v[2:3], v[2:3], 0, s[6:7]

; #define PG8_WAIT_V(n) asm volatile("s_waitcnt vmcnt(" #n ")" ::: "memory")
; template <class Epi, class Sched, bool ALIGN_EPI = false, bool SP2 = false, bool PAIR_ACC = false>
; __device__ __forceinline__ void gemm_phase(PG8_LAS unsigned char* lds, const Gemm g, const Sched& S, const Epi& E) {
;     ...
;     const int tid = tid_, wid = __builtin_amdgcn_readfirstlane(tid >> 6), lane = tid & 63, wr = wid >> 2, wc = wid & 3, fr = lane & 15, fq = lane >> 4;
;     const int K = g.K, nt = K / BK;
;     unsigned voffA[2], voffB[2];
; #pragma unroll
;     for (int i = 0; i < 2; ++i) { int R, C; stage_rc(tid * 16 + i * 8192, R, C); const int Rb = Epi::PERM ? ((R & ~31) + perm32(R & 31)) : R;
;         voffA[i] = (unsigned)(R * K + C) * 2u; voffB[i] = (unsigned)(Rb * K + C) * 2u; }
;     const size_t kstep = (size_t)(BK * 2);
;     const size_t hstep = (size_t)HALF * K * 2;
;     const size_t tstep = 2 * hstep;
;     const unsigned ldsw = (unsigned)wid * 1024u;
;     const int aoff = lds_byte(wr * 64 + fr, fq * 8), boff = lds_byte(wc * 32 + fr, fq * 8);
;     ...
;     Unit cur, nxt; int ui = 0;
;     if (!S.next(0, cur)) return;
;     f32x4 acc[2][2][4][2];
; #pragma unroll
;     for (int a = 0; a < 2; ++a)
; #pragma unroll
;         for (int b = 0; b < 2; ++b)
; #pragma unroll
;             for (int m = 0; m < 4; ++m)
; #pragma unroll
;                 for (int n = 0; n < 2; ++n) acc[a][b][m][n] = (f32x4){0.f, 0.f, 0.f, 0.f};
;     bf16x8 At[4][2], B0[2][2], B1[2][2];
;     const char* cA = (const char*)g.A + (size_t)cur.pm * tstep + (size_t)(cur.pn / g.a_div) * g.a_sel; const char* cB = (const char*)g.Bt + (size_t)cur.pn * tstep;
;     S.a_ready(cur);
;     if constexpr (SP2) {
;         PG8_STAGE(PG8_SB(0, 0), cB, voffB); PG8_STAGE(PG8_SB(0, 1), cB + hstep, voffB); PG8_STAGE(PG8_SA(0, 0), cA, voffA); PG8_STAGE(PG8_SA(0, 1), cA + hstep, voffA);
;         if (wr == 1) PG8_BAR;
;         PG8_WAIT_V(2); PG8_BAR;
;         PG8_STAGE(PG8_SB(1, 0), cB + kstep, voffB); PG8_STAGE(PG8_SA(1, 0), cA + kstep, voffA); PG8_STAGE(PG8_SB(1, 1), cB + hstep + kstep, voffB);
;         PG8_WAIT_V(6); PG8_BAR;
;     } else {
;         PG8_STAGE(PG8_SB(0, 0), cB, voffB); PG8_STAGE(PG8_SA(0, 0), cA, voffA); PG8_STAGE(PG8_SB(0, 1), cB + hstep, voffB); PG8_STAGE(PG8_SA(0, 1), cA + hstep, voffA);
;         if (wr == 1) PG8_BAR;
;         PG8_WAIT_V(4); PG8_BAR;
.LBB0_1075:
	s_andn2_b64 vcc, exec, s[10:11]
	s_cbranch_vccnz .LBB0_1342
	v_ashrrev_i32_e32 v3, 31, v10
	v_lshrrev_b32_e32 v3, 26, v3
	v_add_u32_e32 v3, v10, v3
	v_ashrrev_i32_e32 v11, 6, v3
	v_bfe_i32 v3, v10, 27, 1
	v_lshlrev_b32_e32 v2, 4, v10
	v_lshrrev_b32_e32 v3, 22, v3
	v_add_u32_e32 v3, v2, v3
	v_and_b32_e32 v3, 0xfffffc00, v3
	v_sub_u32_e32 v3, v2, v3
	v_lshrrev_b32_e32 v4, 4, v3
	v_bitop3_b32 v3, v4, v3, 32 bitop3:0x6c
	v_ashrrev_i32_e32 v5, 31, v3
	v_lshrrev_b32_e32 v5, 26, v5
	v_add_u32_e32 v5, v3, v5
	v_lshlrev_b32_e32 v4, 3, v11
	v_ashrrev_i32_e32 v12, 6, v5
	v_and_b32_e32 v5, 0xc0, v5
	v_and_b32_e32 v4, -16, v4
	v_sub_u32_e32 v3, v3, v5
	v_mov_b32_e32 v5, 1
	v_add_u32_e32 v4, v12, v4
	v_ashrrev_i16_sdwa v3, v5, sext(v3) dst_sel:DWORD dst_unused:UNUSED_PAD src0_sel:DWORD src1_sel:BYTE_0
	v_lshlrev_b32_e32 v6, 5, v11
	v_bfe_i32 v13, v3, 0, 16
	v_lshlrev_b32_e32 v3, 1, v4
	v_lshrrev_b32_e32 v7, 2, v4
	v_and_b32_e32 v8, 3, v12
	s_mov_b32 s8, 0x1fffe0
	v_and_b32_e32 v6, 32, v6
	v_and_b32_e32 v3, 24, v3
	v_and_b32_e32 v7, 4, v7
	v_and_or_b32 v8, v4, s8, v8
	v_or3_b32 v3, v8, v7, v3
	v_add_lshl_u32 v6, v6, v13, 1
	v_add_u32_e32 v2, 0x2000, v2
	v_lshl_add_u32 v148, v3, 11, v6
	v_ashrrev_i32_e32 v3, 31, v2
	v_lshrrev_b32_e32 v3, 22, v3
	v_add_u32_e32 v3, v2, v3
	v_ashrrev_i32_e32 v14, 10, v3
	v_mul_i32_i24_e32 v3, 0x400, v14
	s_mov_b64 s[28:29], s[26:27]
	v_sub_u32_e32 v2, v2, v3
	v_lshrrev_b32_e32 v3, 4, v2
	v_bitop3_b32 v2, v3, v2, 32 bitop3:0x6c
	v_lshl_add_u32 v146, v4, 11, v6
	v_ashrrev_i32_e32 v4, 31, v2
	v_lshrrev_b32_e32 v4, 26, v4
	s_waitcnt lgkmcnt(0)
	s_add_u32 s59, s28, 0x2b00000
	v_add_u32_e32 v4, v2, v4
	s_addc_u32 s61, s29, 0
	v_lshlrev_b32_e32 v3, 3, v14
	v_ashrrev_i32_e32 v15, 6, v4
	v_and_b32_e32 v4, 0xc0, v4
	s_add_u32 s63, s28, 0x800000
	v_and_b32_e32 v3, -16, v3
	v_sub_u32_e32 v2, v2, v4
	s_addc_u32 s69, s29, 0
	s_ashr_i32 s5, s4, 6
	v_add_u32_e32 v3, v15, v3
	v_ashrrev_i16_sdwa v2, v5, sext(v2) dst_sel:DWORD dst_unused:UNUSED_PAD src0_sel:DWORD src1_sel:BYTE_0
	v_and_b32_e32 v5, 3, v15
	s_ashr_i32 s15, s14, 31
	s_ashr_i32 s19, s18, 31
	v_and_or_b32 v5, v3, s8, v5
	s_ashr_i32 s8, s4, 8
	s_lshl_b32 s71, s5, 10
	s_lshl_b64 s[10:11], s[14:15], 19
	s_lshl_b64 s[12:13], s[18:19], 19
	s_add_u32 s16, s63, s12
	v_lshlrev_b32_e32 v6, 5, v14
	v_bfe_i32 v16, v2, 0, 16
	v_lshlrev_b32_e32 v2, 1, v3
	v_lshrrev_b32_e32 v4, 2, v3
	s_addc_u32 s17, s69, s13
	s_add_i32 s73, s71, 0
	v_and_b32_e32 v6, 32, v6
	v_and_b32_e32 v2, 24, v2
	v_and_b32_e32 v4, 4, v4
	s_add_i32 m0, s73, 0x10000
	v_or3_b32 v2, v5, v4, v2
	v_add_lshl_u32 v4, v6, v16, 1
	global_load_lds_dwordx4 v148, s[16:17]
	s_add_i32 m0, s73, 0x12000
	v_lshl_add_u32 v152, v2, 11, v4
	s_add_u32 s12, s16, 0x40000
	global_load_lds_dwordx4 v152, s[16:17]
	s_addc_u32 s13, s17, 0
	s_add_i32 m0, s73, 0x14000
	v_lshl_add_u32 v150, v3, 11, v4
	global_load_lds_dwordx4 v148, s[12:13]
	s_add_i32 m0, s73, 0x16000
	v_mov_b32_e32 v155, 0
	global_load_lds_dwordx4 v152, s[12:13]
	s_add_u32 s12, s59, s10
	s_addc_u32 s13, s61, s11
	s_add_i32 s75, s73, 0x2000
	s_mov_b32 m0, s73
	s_add_u32 s10, s12, 0x40000
	global_load_lds_dwordx4 v146, s[12:13]
	s_mov_b32 m0, s75
	s_addc_u32 s11, s13, 0
	s_add_i32 s44, s73, 0x4000
	global_load_lds_dwordx4 v150, s[12:13]
	s_mov_b32 m0, s44
	s_add_i32 s45, s73, 0x6000
	global_load_lds_dwordx4 v146, s[10:11]
	s_mov_b32 m0, s45
	v_mov_b32_e32 v149, v155
	global_load_lds_dwordx4 v150, s[10:11]
	v_mov_b32_e32 v153, v155
	v_mov_b32_e32 v147, v155
	v_mov_b32_e32 v151, v155
	s_cmp_eq_u32 s8, 1
	s_mov_b32 s31, 0
	v_lshl_add_u64 v[8:9], s[16:17], 0, v[148:149]
	v_lshl_add_u64 v[6:7], s[16:17], 0, v[152:153]
	v_lshl_add_u64 v[2:3], s[12:13], 0, v[146:147]
	s_cselect_b64 s[38:39], -1, 0
	s_cmp_lg_u32 s8, 1
	v_lshl_add_u64 v[4:5], s[12:13], 0, v[150:151]
	s_cbranch_scc1 .LBB0_1078
	s_barrier

; #define LAS __attribute__((address_space(3)))
; __device__ __forceinline__ void attn_unit(LAS unsigned char* lds, bf16* Q, const bf16* Kg, const bf16* Vg, const float* snk, int unit, int tid) {
;     const int lane = tid & 63, wave = tid >> 6, fr = lane & 15, fq = lane >> 4;
;     const int b = unit >> 6, n = (unit >> 1) & 31, h = unit & 1, r0 = b * SEQ + n * 128, hq = 8 * h + wave;
;     const v4u zero4 = {0u, 0u, 0u, 0u};
;     bf16* qbase = Q + (size_t)(r0 + fr) * 1024 + hq * 64;
;     bf16x8_t qf[8][2];
; #pragma unroll
;     for (int mt = 0; mt < 8; ++mt) { qf[mt][0] = *(const bf16x8_t*)(qbase + (size_t)mt * 16 * 1024 + 8 * fq); qf[mt][1] = *(const bf16x8_t*)(qbase + (size_t)mt * 16 * 1024 + 32 + 8 * fq); }
; #pragma unroll
;     for (int i = 0; i < 4; ++i) { const int idx = tid + 512 * i, j = idx >> 3, c = idx & 7, p = n * 128 - 128 + j;
;         v4u w = zero4; if (p >= 0) w = *(const v4u*)(Kg + (size_t)(b * SEQ + p) * 128 + h * 64 + c * 8);
;         *(LAS v4u*)(lds + j * ATT_KP + c * 16) = w; }
; #pragma unroll
;     for (int i = 0; i < 2; ++i) { const int idx = tid + 512 * i, j = (idx >> 3) * 2, c = idx & 7, p = n * 128 - 128 + j;
;         v4u w0 = zero4, w1 = zero4;
;         if (p >= 0) { w0 = *(const v4u*)(Vg + (size_t)(b * SEQ + p) * 128 + h * 64 + c * 8); w1 = *(const v4u*)(Vg + (size_t)(b * SEQ + p + 1) * 128 + h * 64 + c * 8); }
;         const unsigned A0[4] = {w0.x, w0.y, w0.z, w0.w}, A1[4] = {w1.x, w1.y, w1.z, w1.w};
; #pragma unroll
;         for (int e = 0; e < 8; ++e) { const unsigned lo = (e & 1) ? (A0[e >> 1] >> 16) : (A0[e >> 1] & 0xffffu), hi = (e & 1) ? (A1[e >> 1] & 0xffff0000u) : (A1[e >> 1] << 16);
;             *(LAS unsigned*)(lds + ATT_VOFF + (8 * c + e) * ATT_VP + j * 2) = lo | hi; } }
;     __syncthreads();
;     const float sink = snk[hq] * 1.4426950408889634f;
;     bool lo_ok[4];
; #pragma unroll
; __global__ void __launch_bounds__(512, 2) fwd_mega(Args a) {
;     ...
;         {
;             int tid_ = threadIdx.x; asm volatile("" : "+v"(tid_));
;             for (int it = bx; it < 512; it += G) {
;                 if (it < 256) attn_unit(lds, WSP(WS_Q), WSP(WS_K), WSP(WS_V), INF(7) + l * 16, it, tid_);
;                 else sgu_unit(lds, WSP(WS_U), WSP(WS_VS), (const float*)(a.ws + WS_SGS), INF(8) + l * 1024, INF(9) + l * 1024, (const v4u*)(a.ws + WS_WF), INF(11) + l * 8 * 128, it - 256, tid_);
;             }
.LBB0_1394:
	s_or_b64 exec, exec, s[6:7]
	v_readlane_b32 s4, v246, 18
	v_readlane_b32 s5, v246, 19
	v_mov_b32_e32 v161, v0
	s_andn2_b64 vcc, exec, s[4:5]
	s_waitcnt lgkmcnt(0)
	s_barrier
	s_cbranch_vccnz .LBB0_1415
	s_movk_i32 s4, 0x80
	v_cmp_gt_i32_e64 s[6:7], s4, v161
	v_ashrrev_i32_e32 v169, 6, v161
	s_movk_i32 s4, 0x4400
	v_mul_lo_u32 v5, v169, s4
	s_mov_b64 s[4:5], s[26:27]
	s_load_dwordx4 s[28:31], s[0:1], 0x38
	s_load_dwordx2 s[16:17], s[0:1], 0x48
	s_load_dwordx2 s[18:19], s[0:1], 0x58
	v_and_b32_e32 v6, 7, v161
	v_add_u32_e32 v8, 0x200, v161
	v_lshlrev_b32_e32 v170, 3, v6
	s_waitcnt lgkmcnt(0)
	s_add_u32 s38, s4, 0x4b00000
	s_addc_u32 s39, s5, 0
	s_add_u32 s30, s30, 0x1000
	s_addc_u32 s31, s31, 0
	s_add_u32 s40, s16, 0x1000
	v_mul_u32_u24_e32 v10, 0x110, v6
	v_bfe_u32 v15, v161, 4, 2
	v_lshlrev_b32_e32 v4, 4, v6
	s_waitcnt vmcnt(1)
	v_mul_u32_u24_e32 v20, 0x1080, v6
	v_ashrrev_i32_e32 v6, 2, v8
	s_addc_u32 s41, s17, 0
	v_add_u32_e32 v9, 0x400, v161
	v_and_b32_e32 v176, -2, v6
	v_lshlrev_b32_e32 v6, 2, v15
	s_add_u32 s44, s18, 0x1000
	v_and_b32_e32 v3, 63, v161
	v_and_b32_e32 v163, 15, v161
	v_ashrrev_i32_e32 v172, 3, v8
	v_ashrrev_i32_e32 v173, 3, v9
	v_add_u32_e32 v9, 0x600, v161
	v_or_b32_e32 v8, 2, v6
	s_addc_u32 s45, s19, 0
	v_mov_b32_e32 v147, 0
	v_ashrrev_i32_e32 v174, 3, v9
	v_ashrrev_i32_e32 v9, 2, v161
	v_cmp_gt_u32_e64 s[12:13], v8, v163
	v_or_b32_e32 v8, 3, v6
	v_lshlrev_b32_e32 v146, 4, v3
	s_add_u32 s46, s4, 0xf400000
	v_add_u32_e32 v3, 0, v5
	v_lshrrev_b32_e32 v5, 1, v161
	v_bfe_u32 v2, v161, 3, 3
	v_and_b32_e32 v175, -2, v9
	v_cmp_gt_u32_e64 s[14:15], v8, v163
	v_lshl_add_u64 v[8:9], s[4:5], 0, v[146:147]
	s_mov_b64 s[16:17], 0x680000
	s_addc_u32 s47, s5, 0
	v_and_b32_e32 v146, 24, v5
	v_lshlrev_b32_e32 v167, 3, v161
	v_lshlrev_b32_e32 v7, 11, v2
	v_lshlrev_b32_e32 v11, 2, v2
	v_lshlrev_b32_e32 v12, 4, v2
	v_bfe_u32 v2, v161, 3, 1
	v_lshl_add_u64 v[148:149], v[8:9], 0, s[16:17]
	v_lshl_add_u64 v[8:9], s[4:5], 0, v[146:147]
	s_mov_b64 s[16:17], 0x9300000
	s_add_u32 s50, s4, 0x6b00000
	v_mov_b32_e32 v5, v147
	v_and_or_b32 v2, v167, 56, v2
	v_lshl_add_u64 v[150:151], v[8:9], 0, s[16:17]
	s_addc_u32 s51, s5, 0
	v_add_u32_e32 v8, 0, v4
	v_lshl_add_u64 v[4:5], s[4:5], 0, v[4:5]
	s_mov_b64 s[4:5], 0x8b00000
	v_mul_u32_u24_e32 v14, 0x110, v2
	v_lshlrev_b32_e32 v2, 3, v15
	v_lshl_add_u64 v[152:153], v[4:5], 0, s[4:5]
	s_mov_b64 s[4:5], 0x8f00000
	v_lshl_add_u32 v9, v15, 4, 0
	v_and_b32_e32 v13, 48, v161
	v_ashrrev_i32_e32 v171, 3, v161
	s_movk_i32 s20, 0x90
	v_add3_u32 v177, v3, v10, v11
	v_lshl_add_u64 v[154:155], v[4:5], 0, s[4:5]
	v_sub_u32_e32 v10, v9, v2
	s_movk_i32 s4, 0x210
	v_mul_lo_u32 v16, v171, s20
	v_mul_lo_u32 v17, v172, s20
	v_mul_lo_u32 v18, v173, s20
	v_mul_lo_u32 v19, v174, s20
	v_add_u32_e32 v3, v3, v13
	v_lshl_add_u32 v4, v175, 1, 0
	v_lshl_add_u32 v5, v176, 1, 0
	v_mad_u32_u24 v179, v163, s4, v10
	s_lshl_b32 s4, s2, 2
	v_ashrrev_i32_e32 v165, 7, v161
	v_and_b32_e32 v168, 64, v161
	v_cmp_gt_u32_e64 s[8:9], v6, v163
	v_cmp_lt_u32_e64 s[10:11], v6, v163
	s_mov_b32 s49, 0
	v_mad_u32_u24 v178, v163, s20, v9
	s_addk_i32 s4, 0xfc00
	s_lshl_b32 s5, s3, 2
	s_lshl_b32 s24, s2, 6
	s_lshl_b32 s25, s3, 6
	s_movk_i32 s34, 0x1000
	s_movk_i32 s35, 0x2000
	s_movk_i32 s36, 0x3000
	s_movk_i32 s37, 0x4000
	s_mov_b32 s52, 0x3a800000
	s_mov_b32 s42, 0x800000
	v_lshlrev_b32_e32 v180, 1, v7
	s_mov_b32 s43, 0x8000
	s_mov_b32 s53, 0x10000
	s_mov_b32 s54, 0x18000
	s_mov_b32 s55, 0x20000
	s_mov_b32 s56, 0x28000
	s_mov_b32 s57, 0x30000
	s_mov_b32 s58, 0x38000
	v_add_u32_e32 v181, 0, v12
	s_mov_b32 s59, 0xffff0000
	v_add_u32_e32 v182, v3, v14
	v_lshlrev_b32_e32 v146, 1, v2
	v_add_u32_e32 v183, v8, v16
	v_add_u32_e32 v184, v8, v17
	v_add_u32_e32 v185, v8, v18
	v_add_u32_e32 v186, v8, v19
	s_mov_b32 s60, 0xffff
	v_add_u32_e32 v187, v4, v20
	v_add_u32_e32 v188, v5, v20
	s_mov_b32 s61, 0x3fb8aa3b
	v_lshlrev_b32_e32 v156, 1, v6
	v_mbcnt_hi_u32_b32 v189, -1, v1
	v_mov_b32_e32 v190, 0xff800000
	s_mov_b32 s62, s2
	s_branch .LBB0_1398

;     __host__ __device__ void init(int M, int N, int G_, int c_) { base.init(M, N, G_, c_); G = G_; c = c_; }
;     __host__ __device__ void init(int M, int G_, int c_) { base.init(M, 1024, G_, c_); }
;     __host__ __device__ bool next(int i, Unit& u) const { Unit b; if (!base.next(i >> 1, b)) return false; u.pm = b.pm; u.pn = b.pn + 4 * (i & 1); return true; }
;     __host__ __device__ bool next(int i, Unit& u) const {
;         const long L = (long)i * G + c; if (L >= nwg) return false;
;         int wgid = (int)L; { const int q = nwg / NXCD, r = nwg % NXCD, xcd = wgid % NXCD, off = wgid / NXCD; wgid = (xcd < r ? xcd * (q + 1) : r * (q + 1) + (xcd - r) * q) + off; }
;         const int nig = WGM * nN, gid = wgid / nig, fm = gid * WGM, gsz = (nM - fm) < WGM ? (nM - fm) : WGM;
;         u.pm = fm + ((wgid % nig) % gsz); u.pn = (wgid % nig) / gsz; return true;
;     }
; __global__ void __launch_bounds__(512, 2) fwd_mega(Args a) {
;     ...
;             pg8::Gemm g{WSP(WS_Q), WSP(WS_PAB), M, 2048, D, 4, (size_t)(WS_U - WS_Q)}; pg8::PairOrder S; S.init(M, G, bx);
;             pg8::EpiMerge E{WSP(WS_MG), WSP(WS_GA), WSP(WS_GB)};
;             pg8::gemm_phase<pg8::EpiMerge, pg8::PairOrder, true, true, true>(lds, g, S, E);
.LBB0_1467:
	s_or_b64 exec, exec, s[6:7]
	s_waitcnt lgkmcnt(0)
	s_barrier
	s_mov_b64 s[6:7], s[26:27]
	v_mov_b32_e32 v10, v0
	s_and_b64 vcc, exec, s[74:75]
	v_readfirstlane_b32 s20, v10
	s_cbranch_vccnz .LBB0_1473
	s_lshr_b32 s4, s65, 29
	s_add_i32 s4, s2, s4
	s_and_b32 s5, s4, -8
	s_sub_i32 s5, s2, s5
	s_cmp_gt_i32 s5, -1
	s_cbranch_scc0 .LBB0_1470
	s_lshl_b32 s10, s5, 5
	s_cbranch_execz .LBB0_1471
	s_branch .LBB0_1472

; #define PG8_BAR __builtin_amdgcn_s_barrier()
; template <class Epi, class Sched, bool ALIGN_EPI = false, bool SP2 = false, bool PAIR_ACC = false>
; __device__ __forceinline__ void gemm_phase(PG8_LAS unsigned char* lds, const Gemm g, const Sched& S, const Epi& E) {
;     ...
;     const int tid = tid_, wid = __builtin_amdgcn_readfirstlane(tid >> 6), lane = tid & 63, wr = wid >> 2, wc = wid & 3, fr = lane & 15, fq = lane >> 4;
;     const int K = g.K, nt = K / BK;
;     unsigned voffA[2], voffB[2];
; #pragma unroll
;     for (int i = 0; i < 2; ++i) { int R, C; stage_rc(tid * 16 + i * 8192, R, C); const int Rb = Epi::PERM ? ((R & ~31) + perm32(R & 31)) : R;
;         voffA[i] = (unsigned)(R * K + C) * 2u; voffB[i] = (unsigned)(Rb * K + C) * 2u; }
;     const size_t kstep = (size_t)(BK * 2);
;     const size_t hstep = (size_t)HALF * K * 2;
;     const size_t tstep = 2 * hstep;
;     const unsigned ldsw = (unsigned)wid * 1024u;
;     const int aoff = lds_byte(wr * 64 + fr, fq * 8), boff = lds_byte(wc * 32 + fr, fq * 8);
;     ...
;     Unit cur, nxt; int ui = 0;
;     if (!S.next(0, cur)) return;
;     f32x4 acc[2][2][4][2];
; #pragma unroll
;     for (int a = 0; a < 2; ++a)
; #pragma unroll
;         for (int b = 0; b < 2; ++b)
; #pragma unroll
;             for (int m = 0; m < 4; ++m)
; #pragma unroll
;                 for (int n = 0; n < 2; ++n) acc[a][b][m][n] = (f32x4){0.f, 0.f, 0.f, 0.f};
;     bf16x8 At[4][2], B0[2][2], B1[2][2];
;     const char* cA = (const char*)g.A + (size_t)cur.pm * tstep + (size_t)(cur.pn / g.a_div) * g.a_sel; const char* cB = (const char*)g.Bt + (size_t)cur.pn * tstep;
;     S.a_ready(cur);
;     if constexpr (SP2) {
;         PG8_STAGE(PG8_SB(0, 0), cB, voffB); PG8_STAGE(PG8_SB(0, 1), cB + hstep, voffB); PG8_STAGE(PG8_SA(0, 0), cA, voffA); PG8_STAGE(PG8_SA(0, 1), cA + hstep, voffA);
;         if (wr == 1) PG8_BAR;
;         PG8_WAIT_V(2); PG8_BAR;
; __global__ void __launch_bounds__(512, 2) fwd_mega(Args a) {
;     ...
;         {
;             pg8::Gemm g{WSP(WS_H2), WSP(WS_WGU), M, 2 * FF, D, 1 << 20, 0}; pg8::StaticOrder S; S.init(M, 2 * FF, G, bx);
;             pg8::EpiGUConv E{WSP(WS_ACT), (float*)(a.ws + WS_RAWA), (float*)(a.ws + WS_RAWU), (float*)(a.ws + WS_TAILA), INF(18) + (size_t)l * 3 * FF, INF(19) + (size_t)l * FF, lds + XCH_OFF};
;             pg8::gemm_phase<pg8::EpiGUConv, pg8::StaticOrder, true, true>(lds, g, S, E);
.LBB0_1728:
	s_or_b64 exec, exec, s[6:7]
	v_readlane_b32 s4, v246, 16
	v_mov_b32_e32 v12, v0
	v_readlane_b32 s5, v246, 17
	s_waitcnt lgkmcnt(0)
	s_barrier
	s_andn2_b64 vcc, exec, s[4:5]
	v_readfirstlane_b32 s42, v12
	s_cbranch_vccnz .LBB0_1753
	v_lshlrev_b32_e32 v2, 4, v12
	v_add_u32_e32 v3, 0x2000, v2
	v_ashrrev_i32_e32 v4, 31, v3
	v_lshrrev_b32_e32 v4, 22, v4
	v_add_u32_e32 v4, v3, v4
	v_ashrrev_i32_e32 v10, 10, v4
	v_mul_i32_i24_e32 v4, 0x400, v10
	v_sub_u32_e32 v3, v3, v4
	v_lshrrev_b32_e32 v4, 4, v3
	v_bitop3_b32 v3, v4, v3, 32 bitop3:0x6c
	v_ashrrev_i32_e32 v4, 31, v3
	v_lshrrev_b32_e32 v4, 26, v4
	v_add_u32_e32 v4, v3, v4
	v_lshlrev_b32_e32 v5, 3, v10
	v_ashrrev_i32_e32 v11, 6, v4
	v_and_b32_e32 v5, -16, v5
	v_add_u32_e32 v5, v11, v5
	v_and_b32_e32 v6, 3, v11
	s_mov_b32 s8, 0x1fffe0
	v_lshrrev_b32_e32 v7, 2, v5
	v_lshlrev_b32_e32 v8, 1, v5
	v_and_b32_e32 v4, 0xc0, v4
	v_and_or_b32 v6, v5, s8, v6
	v_and_b32_e32 v7, 4, v7
	v_and_b32_e32 v8, 24, v8
	v_sub_u32_e32 v3, v3, v4
	v_mov_b32_e32 v4, 1
	v_or3_b32 v6, v6, v7, v8
	v_lshlrev_b32_e32 v7, 5, v10
	v_ashrrev_i16_sdwa v3, v4, sext(v3) dst_sel:DWORD dst_unused:UNUSED_PAD src0_sel:DWORD src1_sel:BYTE_0
	v_and_b32_e32 v7, 32, v7
	v_bfe_i32 v13, v3, 0, 16
	v_add_lshl_u32 v3, v7, v13, 1
	v_lshl_add_u32 v172, v6, 11, v3
	v_lshl_add_u32 v174, v5, 11, v3
	v_bfe_i32 v3, v12, 27, 1
	v_lshrrev_b32_e32 v3, 22, v3
	v_add_u32_e32 v3, v2, v3
	v_and_b32_e32 v3, 0xfffffc00, v3
	s_mov_b64 s[6:7], s[26:27]
	v_sub_u32_e32 v2, v2, v3
	v_lshrrev_b32_e32 v3, 4, v2
	v_ashrrev_i32_e32 v5, 31, v12
	v_bitop3_b32 v2, v3, v2, 32 bitop3:0x6c
	v_lshrrev_b32_e32 v5, 26, v5
	v_ashrrev_i32_e32 v3, 31, v2
	v_add_u32_e32 v5, v12, v5
	v_lshrrev_b32_e32 v3, 26, v3
	v_ashrrev_i32_e32 v15, 6, v5
	s_waitcnt lgkmcnt(0)
	s_add_u32 s4, s6, 0x4b00000
	v_add_u32_e32 v3, v2, v3
	v_lshlrev_b32_e32 v5, 3, v15
	s_addc_u32 s5, s7, 0
	v_ashrrev_i32_e32 v14, 6, v3
	v_and_b32_e32 v5, -16, v5
	s_add_u32 s24, s6, 0x1a80000
	v_add_u32_e32 v5, v14, v5
	v_and_b32_e32 v6, 3, v14
	s_addc_u32 s25, s7, 0
	v_and_or_b32 v6, v5, s8, v6
	s_lshr_b32 s8, s65, 29
	s_add_i32 s8, s2, s8
	s_ashr_i32 s30, s42, 6
	s_ashr_i32 s9, s8, 3
	s_and_b32 s8, s8, -8
	s_ashr_i32 s44, s42, 8
	s_lshl_b32 s34, s30, 10
	s_sub_i32 s8, s2, s8
	s_cmp_lt_i32 s8, 0
	s_movk_i32 s35, 0xb1
	s_cselect_b32 s10, s35, 0xb0
	s_mul_i32 s8, s10, s8
	s_add_i32 s8, s8, s9
	s_mul_hi_i32 s9, s8, 0x2e8ba2e9
	s_lshr_b32 s10, s9, 31
	s_ashr_i32 s9, s9, 5
	s_add_i32 s9, s9, s10
	s_lshl_b32 s10, s9, 3
	s_mulk_i32 s9, 0xb0
	s_sub_i32 s8, s8, s9
	s_sext_i32_i16 s9, s8
	s_bfe_u32 s9, s9, 0x3001c
	s_add_i32 s9, s8, s9
	s_sext_i32_i16 s11, s9
	s_and_b32 s9, s9, 0xfff8
	s_sub_i32 s8, s8, s9
	s_sext_i32_i16 s8, s8
	v_lshrrev_b32_e32 v7, 2, v5
	v_lshlrev_b32_e32 v8, 1, v5
	v_and_b32_e32 v3, 0xc0, v3
	s_lshr_b32 s38, s11, 3
	s_add_i32 s58, s10, s8
	v_and_b32_e32 v7, 4, v7
	v_and_b32_e32 v8, 24, v8
	v_sub_u32_e32 v2, v2, v3
	s_ashr_i32 s59, s58, 31
	s_bfe_i64 s[10:11], s[38:39], 0x100000
	v_or3_b32 v6, v6, v7, v8
	v_lshlrev_b32_e32 v7, 5, v15
	v_ashrrev_i16_sdwa v2, v4, sext(v2) dst_sel:DWORD dst_unused:UNUSED_PAD src0_sel:DWORD src1_sel:BYTE_0
	s_lshl_b64 s[8:9], s[58:59], 19
	s_lshl_b64 s[10:11], s[10:11], 19
	v_and_b32_e32 v7, 32, v7
	v_bfe_i32 v16, v2, 0, 16
	s_add_u32 s60, s24, s10
	v_add_lshl_u32 v2, v7, v16, 1
	s_addc_u32 s61, s25, s11
	s_add_i32 s36, s34, 0
	v_lshl_add_u32 v176, v6, 11, v2
	s_add_i32 m0, s36, 0x10000
	v_lshl_add_u32 v178, v5, 11, v2
	global_load_lds_dwordx4 v176, s[60:61]
	s_add_i32 m0, s36, 0x12000
	s_add_u32 s10, s60, 0x40000
	global_load_lds_dwordx4 v172, s[60:61]
	s_addc_u32 s11, s61, 0
	s_add_i32 m0, s36, 0x14000
	v_mov_b32_e32 v177, 0
	global_load_lds_dwordx4 v176, s[10:11]
	s_add_i32 m0, s36, 0x16000
	s_add_u32 s62, s4, s8
	s_addc_u32 s63, s5, s9
	s_add_i32 s37, s36, 0x2000
	global_load_lds_dwordx4 v172, s[10:11]
	s_mov_b32 m0, s36
	s_add_u32 s8, s62, 0x40000
	global_load_lds_dwordx4 v178, s[62:63]
	s_mov_b32 m0, s37
	s_addc_u32 s9, s63, 0
	s_add_i32 s49, s36, 0x4000
	global_load_lds_dwordx4 v174, s[62:63]
	s_mov_b32 m0, s49
	s_add_i32 s64, s36, 0x6000
	global_load_lds_dwordx4 v178, s[8:9]
	s_mov_b32 m0, s64
	v_mov_b32_e32 v173, v177
	global_load_lds_dwordx4 v174, s[8:9]
	s_load_dwordx4 s[8:11], s[0:1], 0x90
	v_mov_b32_e32 v179, v177
	v_mov_b32_e32 v175, v177
	s_cmp_eq_u32 s44, 1
	s_mov_b32 s66, 0
	v_lshl_add_u64 v[8:9], s[60:61], 0, v[176:177]
	v_lshl_add_u64 v[6:7], s[60:61], 0, v[172:173]
	v_lshl_add_u64 v[2:3], s[62:63], 0, v[178:179]
	s_cselect_b64 s[12:13], -1, 0
	s_cmp_lg_u32 s44, 1
	v_lshl_add_u64 v[4:5], s[62:63], 0, v[174:175]
	s_cbranch_scc1 .LBB0_1731
	s_barrier
